# P5 conv section rescheduled (temp renaming, hazard pads re-derived: 378 -> 122 s_nop) on top of the token/row-sum-table version
# speedup vs baseline: 1.0383x; 1.0045x over previous
.LBB0_585:
	s_or_b64 exec, exec, s[62:63]
	v_add_co_u32_e32 v28, vcc, s78, v242
	v_add_f32_e32 v24, v240, v253
	s_nop 0
	v_addc_co_u32_e32 v29, vcc, 0, v243, vcc
	v_add_co_u32_e32 v36, vcc, s78, v238
	v_fmamk_f32 v24, v24, 0x3a800000, v249
	s_nop 0
	v_addc_co_u32_e32 v37, vcc, 0, v239, vcc
	v_add_co_u32_e32 v38, vcc, s93, v238
	s_waitcnt lgkmcnt(0)
	s_barrier
	v_addc_co_u32_e32 v39, vcc, 0, v239, vcc
	v_add_co_u32_e32 v44, vcc, s82, v238
	v_rsq_f32_e32 v240, v24
	s_nop 0
	v_addc_co_u32_e32 v45, vcc, 0, v239, vcc
	v_add_co_u32_e32 v46, vcc, s92, v238
	global_load_dwordx4 v[24:27], v[242:243], off offset:16
	global_load_dwordx4 v[32:35], v[28:29], off offset:3088
	v_addc_co_u32_e32 v47, vcc, 0, v239, vcc
	v_add_co_u32_e32 v52, vcc, s94, v238
	global_load_dwordx4 v[28:31], v[238:239], off offset:16
	global_load_dwordx4 v[40:43], v[36:37], off offset:3088
	v_addc_co_u32_e32 v53, vcc, 0, v239, vcc
	global_load_dwordx4 v[36:39], v[38:39], off offset:2064
	global_load_dwordx4 v[48:51], v[44:45], off offset:1040
	global_load_dwordx4 v[44:47], v[46:47], off offset:16
	v_add_f32_e32 v202, v223, v225
	global_load_dwordx4 v[52:55], v[52:53], off offset:3088
	v_pk_mul_f32 v[154:155], v[154:155], v[240:241] op_sel_hi:[1,0]
	v_fmamk_f32 v227, v202, 0x3a800000, v249
	v_pk_mul_f32 v[152:153], v[152:153], v[240:241] op_sel_hi:[1,0]
	v_pk_mul_f32 v[166:167], v[166:167], v[240:241] op_sel_hi:[1,0]
	v_rsq_f32_e32 v238, v227
	v_pk_mul_f32 v[164:165], v[164:165], v[240:241] op_sel_hi:[1,0]
	v_pk_mul_f32 v[160:161], v[160:161], v[238:239] op_sel_hi:[1,0]
	v_pk_mul_f32 v[156:157], v[156:157], v[238:239] op_sel_hi:[1,0]
	v_pk_mul_f32 v[162:163], v[162:163], v[238:239] op_sel_hi:[1,0]
	v_mov_b32_dpp v227, v160 row_ror:1 row_mask:0xf bank_mask:0xf
	v_mov_b32_dpp v223, v160 row_ror:2 row_mask:0xf bank_mask:0xf
	v_mov_b32_dpp v225, v156 row_ror:2 row_mask:0xf bank_mask:0xf
	v_mov_b32_dpp v227, v184 row_shr:1 row_mask:0xf bank_mask:0xf
	v_mov_b32_dpp v223, v184 row_shr:2 row_mask:0xf bank_mask:0xf
	v_mov_b32_dpp v225, v188 row_shr:2 row_mask:0xf bank_mask:0xf
	v_pk_mul_f32 v[158:159], v[158:159], v[238:239] op_sel_hi:[1,0]
	v_fma_f32 v248, v140, v223, v120
	v_fma_f32 v239, v128, v225, v124
	v_fmac_f32_e32 v248, v144, v227
	v_mov_b32_dpp v227, v156 row_ror:1 row_mask:0xf bank_mask:0xf
	v_fmac_f32_e32 v248, v148, v184
	s_nop 0
	v_mov_b32_dpp v227, v188 row_shr:1 row_mask:0xf bank_mask:0xf
	v_mul_f32_e32 v253, 0xbfb8aa3b, v248
	v_fmac_f32_e32 v239, v132, v227
	v_mov_b32_dpp v227, v161 row_ror:2 row_mask:0xf bank_mask:0xf
	v_exp_f32_e32 v254, v253
	v_fmac_f32_e32 v239, v136, v188
	v_mov_b32_dpp v188, v161 row_ror:1 row_mask:0xf bank_mask:0xf
	v_add_f32_e32 v242, 1.0, v254
	v_mov_b32_dpp v227, v185 row_shr:2 row_mask:0xf bank_mask:0xf
	v_mov_b32_dpp v188, v185 row_shr:1 row_mask:0xf bank_mask:0xf
	v_rcp_f32_e32 v243, v242
	v_fma_f32 v223, v141, v227, v121
	v_mul_f32_e32 v202, v248, v243
	v_fmac_f32_e32 v223, v145, v188
	v_mov_b32_dpp v188, v157 row_ror:1 row_mask:0xf bank_mask:0xf
	v_mul_f32_e32 v184, v239, v202
	v_fmac_f32_e32 v223, v149, v185
	v_mov_b32_dpp v188, v189 row_shr:1 row_mask:0xf bank_mask:0xf
	v_mov_b32_dpp v248, v157 row_ror:2 row_mask:0xf bank_mask:0xf
	v_mul_f32_e32 v253, 0xbfb8aa3b, v223
	s_nop 0
	v_mov_b32_dpp v248, v189 row_shr:2 row_mask:0xf bank_mask:0xf
	v_exp_f32_e32 v254, v253
	v_fma_f32 v243, v129, v248, v125
	v_add_f32_e32 v242, 1.0, v254
	v_fmac_f32_e32 v243, v133, v188
	v_mov_b32_dpp v188, v162 row_ror:1 row_mask:0xf bank_mask:0xf
	v_rcp_f32_e32 v225, v242
	v_fmac_f32_e32 v243, v137, v189
	v_mov_b32_dpp v188, v186 row_shr:1 row_mask:0xf bank_mask:0xf
	v_mul_f32_e32 v202, v223, v225
	v_mov_b32_dpp v189, v162 row_ror:2 row_mask:0xf bank_mask:0xf
	v_mov_b32_dpp v223, v158 row_ror:2 row_mask:0xf bank_mask:0xf
	v_mul_f32_e32 v185, v243, v202
	v_mov_b32_dpp v189, v186 row_shr:2 row_mask:0xf bank_mask:0xf
	v_mov_b32_dpp v223, v190 row_shr:2 row_mask:0xf bank_mask:0xf
	v_fma_f32 v239, v142, v189, v122
	v_fma_f32 v248, v130, v223, v126
	v_fmac_f32_e32 v239, v146, v188
	v_mov_b32_dpp v188, v158 row_ror:1 row_mask:0xf bank_mask:0xf
	v_fmac_f32_e32 v239, v150, v186
	s_nop 0
	v_mov_b32_dpp v188, v190 row_shr:1 row_mask:0xf bank_mask:0xf
	v_mul_f32_e32 v227, 0xbfb8aa3b, v239
	v_fmac_f32_e32 v248, v134, v188
	v_mov_b32_dpp v188, v163 row_ror:1 row_mask:0xf bank_mask:0xf
	v_exp_f32_e32 v253, v227
	v_fmac_f32_e32 v248, v138, v190
	v_mov_b32_dpp v188, v187 row_shr:1 row_mask:0xf bank_mask:0xf
	v_add_f32_e32 v254, 1.0, v253
	v_mov_b32_dpp v190, v159 row_ror:2 row_mask:0xf bank_mask:0xf
	v_rcp_f32_e32 v242, v254
	s_nop 0
	v_mov_b32_dpp v190, v191 row_shr:2 row_mask:0xf bank_mask:0xf
	v_mul_f32_e32 v225, v239, v242
	v_mov_b32_dpp v239, v163 row_ror:2 row_mask:0xf bank_mask:0xf
	v_fma_f32 v254, v131, v190, v127
	v_mul_f32_e32 v243, v248, v225
	v_mov_b32_dpp v239, v187 row_shr:2 row_mask:0xf bank_mask:0xf
	v_fma_f32 v202, v143, v239, v123
	v_fmac_f32_e32 v202, v147, v188
	v_mov_b32_dpp v188, v159 row_ror:1 row_mask:0xf bank_mask:0xf
	v_fmac_f32_e32 v202, v151, v187
	s_nop 0
	v_mov_b32_dpp v188, v191 row_shr:1 row_mask:0xf bank_mask:0xf
	v_mul_f32_e32 v189, 0xbfb8aa3b, v202
	v_fmac_f32_e32 v254, v135, v188
	v_mov_b32_dpp v188, v164 row_ror:1 row_mask:0xf bank_mask:0xf
	v_exp_f32_e32 v186, v189
	v_fmac_f32_e32 v254, v139, v191
	v_mov_b32_dpp v188, v160 row_shr:1 row_mask:0xf bank_mask:0xf
	v_add_f32_e32 v227, 1.0, v186
	v_rcp_f32_e32 v253, v227
	s_nop 0
	v_mul_f32_e32 v223, v202, v253
	v_mov_b32_dpp v202, v164 row_ror:2 row_mask:0xf bank_mask:0xf
	v_mul_f32_e32 v242, v254, v223
	s_nop 0
	v_mov_b32_dpp v202, v160 row_shr:2 row_mask:0xf bank_mask:0xf
	v_mov_b32_dpp v254, v152 row_ror:2 row_mask:0xf bank_mask:0xf
	v_fma_f32 v225, v140, v202, v120
	s_nop 0
	v_mov_b32_dpp v254, v156 row_shr:2 row_mask:0xf bank_mask:0xf
	v_fmac_f32_e32 v225, v144, v188
	v_mov_b32_dpp v188, v152 row_ror:1 row_mask:0xf bank_mask:0xf
	v_fma_f32 v186, v128, v254, v124
	v_fmac_f32_e32 v225, v148, v160
	v_mov_b32_dpp v188, v156 row_shr:1 row_mask:0xf bank_mask:0xf
	v_mul_f32_e32 v248, 0xbfb8aa3b, v225
	v_fmac_f32_e32 v186, v132, v188
	v_exp_f32_e32 v239, v248
	v_fmac_f32_e32 v186, v136, v156
	v_add_f32_e32 v187, 1.0, v239
	v_rcp_f32_e32 v189, v187
	s_nop 0
	v_mul_f32_e32 v227, v225, v189
	v_mov_b32_dpp v189, v165 row_ror:2 row_mask:0xf bank_mask:0xf
	v_mov_b32_dpp v225, v153 row_ror:2 row_mask:0xf bank_mask:0xf
	v_mul_f32_e32 v188, v186, v227
	v_mov_b32_dpp v227, v165 row_ror:1 row_mask:0xf bank_mask:0xf
	v_mov_b32_dpp v189, v161 row_shr:2 row_mask:0xf bank_mask:0xf
	v_mov_b32_dpp v225, v157 row_shr:2 row_mask:0xf bank_mask:0xf
	v_mov_b32_dpp v227, v161 row_shr:1 row_mask:0xf bank_mask:0xf
	v_fma_f32 v191, v141, v189, v121
	v_fma_f32 v160, v129, v225, v125
	v_fmac_f32_e32 v191, v145, v227
	v_fmac_f32_e32 v191, v149, v161
	v_mov_b32_dpp v161, v153 row_ror:1 row_mask:0xf bank_mask:0xf
	v_mul_f32_e32 v190, 0xbfb8aa3b, v191
	s_nop 0
	v_mov_b32_dpp v161, v157 row_shr:1 row_mask:0xf bank_mask:0xf
	v_exp_f32_e32 v253, v190
	v_fmac_f32_e32 v160, v133, v161
	v_mov_b32_dpp v161, v154 row_ror:2 row_mask:0xf bank_mask:0xf
	v_add_f32_e32 v223, 1.0, v253
	v_fmac_f32_e32 v160, v137, v157
	v_mov_b32_dpp v157, v166 row_ror:2 row_mask:0xf bank_mask:0xf
	v_rcp_f32_e32 v202, v223
	s_nop 0
	v_mov_b32_dpp v157, v162 row_shr:2 row_mask:0xf bank_mask:0xf
	v_mov_b32_dpp v161, v158 row_shr:2 row_mask:0xf bank_mask:0xf
	v_mul_f32_e32 v248, v191, v202
	v_mov_b32_dpp v191, v154 row_ror:1 row_mask:0xf bank_mask:0xf
	v_fma_f32 v239, v142, v157, v122
	v_mul_f32_e32 v187, v160, v248
	v_mov_b32_dpp v248, v166 row_ror:1 row_mask:0xf bank_mask:0xf
	v_mov_b32_dpp v191, v158 row_shr:1 row_mask:0xf bank_mask:0xf
	v_fma_f32 v186, v130, v161, v126
	v_mov_b32_dpp v248, v162 row_shr:1 row_mask:0xf bank_mask:0xf
	v_fmac_f32_e32 v186, v134, v191
	v_fmac_f32_e32 v239, v146, v248
	v_mov_b32_dpp v191, v155 row_ror:2 row_mask:0xf bank_mask:0xf
	v_fmac_f32_e32 v186, v138, v158
	v_fmac_f32_e32 v239, v150, v162
	v_mov_b32_dpp v158, v155 row_ror:1 row_mask:0xf bank_mask:0xf
	v_mov_b32_dpp v191, v159 row_shr:2 row_mask:0xf bank_mask:0xf
	v_mul_f32_e32 v254, 0xbfb8aa3b, v239
	v_mov_b32_dpp v158, v159 row_shr:1 row_mask:0xf bank_mask:0xf
	v_fma_f32 v160, v131, v191, v127
	v_exp_f32_e32 v156, v254
	v_fmac_f32_e32 v160, v135, v158
	v_mov_b32_dpp v158, v180 row_ror:1 row_mask:0xf bank_mask:0xf
	v_add_f32_e32 v189, 1.0, v156
	v_fmac_f32_e32 v160, v139, v159
	v_mov_b32_dpp v158, v152 row_shr:1 row_mask:0xf bank_mask:0xf
	v_rcp_f32_e32 v227, v189
	v_mov_b32_dpp v159, v180 row_ror:2 row_mask:0xf bank_mask:0xf
	v_mul_f32_e32 v253, v239, v227
	v_mov_b32_dpp v239, v167 row_ror:2 row_mask:0xf bank_mask:0xf
	v_mov_b32_dpp v159, v152 row_shr:2 row_mask:0xf bank_mask:0xf
	v_mul_f32_e32 v190, v186, v253
	v_mov_b32_dpp v253, v167 row_ror:1 row_mask:0xf bank_mask:0xf
	v_mov_b32_dpp v239, v163 row_shr:2 row_mask:0xf bank_mask:0xf
	v_fma_f32 v189, v128, v159, v124
	v_mov_b32_dpp v253, v163 row_shr:1 row_mask:0xf bank_mask:0xf
	v_fma_f32 v223, v143, v239, v123
	v_fmac_f32_e32 v189, v132, v158
	v_mov_b32_dpp v158, v181 row_ror:2 row_mask:0xf bank_mask:0xf
	v_fmac_f32_e32 v223, v147, v253
	v_fmac_f32_e32 v189, v136, v152
	v_mov_b32_dpp v158, v153 row_shr:2 row_mask:0xf bank_mask:0xf
	v_fmac_f32_e32 v223, v151, v163
	v_mul_f32_e32 v225, 0xbfb8aa3b, v223
	v_exp_f32_e32 v202, v225
	s_nop 0
	v_add_f32_e32 v157, 1.0, v202
	v_rcp_f32_e32 v248, v157
	s_nop 0
	v_mul_f32_e32 v162, v223, v248
	v_mov_b32_dpp v223, v176 row_ror:2 row_mask:0xf bank_mask:0xf
	v_fma_f32 v248, v129, v158, v125
	v_mul_f32_e32 v191, v160, v162
	v_mov_b32_dpp v162, v176 row_ror:1 row_mask:0xf bank_mask:0xf
	v_mov_b32_dpp v223, v164 row_shr:2 row_mask:0xf bank_mask:0xf
	s_nop 0
	v_mov_b32_dpp v162, v164 row_shr:1 row_mask:0xf bank_mask:0xf
	v_fma_f32 v254, v140, v223, v120
	v_fmac_f32_e32 v254, v144, v162
	v_fmac_f32_e32 v254, v148, v164
	v_mul_f32_e32 v161, 0xbfb8aa3b, v254
	v_exp_f32_e32 v156, v161
	s_nop 0
	v_add_f32_e32 v227, 1.0, v156
	v_rcp_f32_e32 v186, v227
	s_nop 0
	v_mul_f32_e32 v239, v254, v186
	v_mov_b32_dpp v186, v177 row_ror:2 row_mask:0xf bank_mask:0xf
	v_mov_b32_dpp v254, v181 row_ror:1 row_mask:0xf bank_mask:0xf
	v_mul_f32_e32 v202, v189, v239
	v_mov_b32_dpp v239, v177 row_ror:1 row_mask:0xf bank_mask:0xf
	v_mov_b32_dpp v186, v165 row_shr:2 row_mask:0xf bank_mask:0xf
	v_mov_b32_dpp v254, v153 row_shr:1 row_mask:0xf bank_mask:0xf
	v_mov_b32_dpp v239, v165 row_shr:1 row_mask:0xf bank_mask:0xf
	v_fma_f32 v253, v141, v186, v121
	v_fmac_f32_e32 v248, v133, v254
	v_mov_b32_dpp v254, v182 row_ror:2 row_mask:0xf bank_mask:0xf
	v_fmac_f32_e32 v253, v145, v239
	v_fmac_f32_e32 v248, v137, v153
	v_mov_b32_dpp v153, v178 row_ror:2 row_mask:0xf bank_mask:0xf
	v_fmac_f32_e32 v253, v149, v165
	v_mov_b32_dpp v254, v154 row_shr:2 row_mask:0xf bank_mask:0xf
	v_mov_b32_dpp v153, v166 row_shr:2 row_mask:0xf bank_mask:0xf
	v_mul_f32_e32 v225, 0xbfb8aa3b, v253
	v_fma_f32 v152, v130, v254, v126
	v_fma_f32 v164, v142, v153, v122
	v_exp_f32_e32 v157, v225
	s_nop 0
	v_add_f32_e32 v160, 1.0, v157
	v_rcp_f32_e32 v223, v160
	s_nop 0
	v_mul_f32_e32 v162, v253, v223
	v_mov_b32_dpp v253, v182 row_ror:1 row_mask:0xf bank_mask:0xf
	v_mul_f32_e32 v223, v248, v162
	v_mov_b32_dpp v162, v178 row_ror:1 row_mask:0xf bank_mask:0xf
	v_mov_b32_dpp v253, v154 row_shr:1 row_mask:0xf bank_mask:0xf
	s_nop 0
	v_mov_b32_dpp v162, v166 row_shr:1 row_mask:0xf bank_mask:0xf
	v_fmac_f32_e32 v152, v134, v253
	v_mov_b32_dpp v253, v183 row_ror:2 row_mask:0xf bank_mask:0xf
	v_fmac_f32_e32 v164, v146, v162
	v_fmac_f32_e32 v152, v138, v154
	v_mov_b32_dpp v154, v183 row_ror:1 row_mask:0xf bank_mask:0xf
	v_fmac_f32_e32 v164, v150, v166
	v_mov_b32_dpp v253, v155 row_shr:2 row_mask:0xf bank_mask:0xf
	v_mov_b32_dpp v154, v155 row_shr:1 row_mask:0xf bank_mask:0xf
	v_mul_f32_e32 v161, 0xbfb8aa3b, v164
	v_fma_f32 v158, v131, v253, v127
	v_exp_f32_e32 v159, v161
	v_fmac_f32_e32 v158, v135, v154
	v_mov_b32_e32 v161, 0
	v_add_f32_e32 v156, 1.0, v159
	v_fmac_f32_e32 v158, v139, v155
	v_mov_b32_e32 v159, 0
	v_rcp_f32_e32 v227, v156
	v_mov_b32_e32 v154, 0
	v_mov_b32_e32 v155, 0
	v_mul_f32_e32 v189, v164, v227
	v_mov_b32_dpp v164, v179 row_ror:2 row_mask:0xf bank_mask:0xf
	v_mov_b32_e32 v156, 0
	v_mul_f32_e32 v225, v152, v189
	v_mov_b32_dpp v189, v179 row_ror:1 row_mask:0xf bank_mask:0xf
	v_mov_b32_dpp v164, v167 row_shr:2 row_mask:0xf bank_mask:0xf
	v_mov_b32_e32 v152, 0
	v_mov_b32_dpp v189, v167 row_shr:1 row_mask:0xf bank_mask:0xf
	v_fma_f32 v186, v143, v164, v123
	v_fmac_f32_e32 v186, v147, v189
	v_fmac_f32_e32 v186, v151, v167
	v_mul_f32_e32 v239, 0xbfb8aa3b, v186
	v_exp_f32_e32 v165, v239
	s_nop 0
	v_add_f32_e32 v157, 1.0, v165
	v_rcp_f32_e32 v160, v157
	v_mov_b32_e32 v157, 0
	v_mul_f32_e32 v248, v186, v160
	v_mov_b32_e32 v160, 0
	v_mul_f32_e32 v227, v158, v248
	v_mov_b32_e32 v158, 0
	s_and_saveexec_b64 s[58:59], s[36:37]
	s_cbranch_execz .LBB0_587
	ds_read_b128 v[158:161], v207
	ds_read_b128 v[154:157], v207 offset:512
.LBB0_587:
	s_or_b64 exec, exec, s[58:59]
	v_add_f32_e32 v153, v229, v231
	v_add_f32_e32 v166, v233, v241
	v_fmamk_f32 v162, v153, 0x3a800000, v249
	v_fmamk_f32 v254, v166, 0x3a800000, v249
	v_rsq_f32_e32 v164, v162
	v_rsq_f32_e32 v162, v254
	v_pk_mul_f32 v[114:115], v[114:115], v[164:165] op_sel_hi:[1,0]
	v_pk_mul_f32 v[112:113], v[112:113], v[164:165] op_sel_hi:[1,0]
	v_pk_mul_f32 v[102:103], v[102:103], v[164:165] op_sel_hi:[1,0]
	v_pk_mul_f32 v[166:167], v[104:105], v[162:163] op_sel_hi:[1,0]
	v_pk_mul_f32 v[104:105], v[96:97], v[162:163] op_sel_hi:[1,0]
	s_waitcnt lgkmcnt(1)
	v_mov_b32_dpp v97, v158 row_ror:1 row_mask:0xf bank_mask:0xf
	v_mov_b32_dpp v254, v158 row_ror:2 row_mask:0xf bank_mask:0xf
	v_add_f32_e32 v189, v235, v252
	v_mov_b32_dpp v97, v176 row_shr:1 row_mask:0xf bank_mask:0xf
	v_mov_b32_dpp v254, v176 row_shr:2 row_mask:0xf bank_mask:0xf
	v_fmamk_f32 v253, v189, 0x3a800000, v249
	v_pk_mul_f32 v[106:107], v[106:107], v[162:163] op_sel_hi:[1,0]
	v_fma_f32 v239, v140, v254, v120
	v_rsq_f32_e32 v96, v253
	v_fmac_f32_e32 v239, v144, v97
	v_pk_mul_f32 v[98:99], v[98:99], v[162:163] op_sel_hi:[1,0]
	v_fmac_f32_e32 v239, v148, v176
	v_mul_f32_e32 v165, 0xbfb8aa3b, v239
	v_exp_f32_e32 v186, v165
	s_waitcnt lgkmcnt(0)
	v_mov_b32_dpp v158, v154 row_ror:1 row_mask:0xf bank_mask:0xf
	v_pk_mul_f32 v[94:95], v[94:95], v[96:97] op_sel_hi:[1,0]
	v_add_f32_e32 v248, 1.0, v186
	v_mov_b32_dpp v158, v180 row_shr:1 row_mask:0xf bank_mask:0xf
	v_mov_b32_dpp v163, v154 row_ror:2 row_mask:0xf bank_mask:0xf
	v_rcp_f32_e32 v153, v248
	s_nop 0
	v_mov_b32_dpp v163, v180 row_shr:2 row_mask:0xf bank_mask:0xf
	v_pk_mul_f32 v[100:101], v[100:101], v[164:165] op_sel_hi:[1,0]
	v_mul_f32_e32 v252, v239, v153
	v_fma_f32 v241, v128, v163, v124
	v_mov_b32_dpp v239, v159 row_ror:2 row_mask:0xf bank_mask:0xf
	v_pk_mul_f32 v[92:93], v[92:93], v[96:97] op_sel_hi:[1,0]
	v_fmac_f32_e32 v241, v132, v158
	v_mov_b32_dpp v239, v177 row_shr:2 row_mask:0xf bank_mask:0xf
	v_pk_mul_f32 v[90:91], v[90:91], v[96:97] op_sel_hi:[1,0]
	v_fmac_f32_e32 v241, v136, v180
	v_fma_f32 v97, v141, v239, v121
	v_pk_mul_f32 v[88:89], v[88:89], v[96:97] op_sel_hi:[1,0]
	v_mul_f32_e32 v254, v241, v252
	v_mov_b32_dpp v252, v159 row_ror:1 row_mask:0xf bank_mask:0xf
	v_mov_b32_dpp v241, v155 row_ror:1 row_mask:0xf bank_mask:0xf
	v_mov_b32_dpp v159, v155 row_ror:2 row_mask:0xf bank_mask:0xf
	v_mov_b32_dpp v252, v177 row_shr:1 row_mask:0xf bank_mask:0xf
	v_mov_b32_dpp v241, v181 row_shr:1 row_mask:0xf bank_mask:0xf
	v_mov_b32_dpp v159, v181 row_shr:2 row_mask:0xf bank_mask:0xf
	v_fmac_f32_e32 v97, v145, v252
	v_fma_f32 v253, v129, v159, v125
	v_fmac_f32_e32 v97, v149, v177
	v_fmac_f32_e32 v253, v133, v241
	v_mul_f32_e32 v176, 0xbfb8aa3b, v97
	v_mov_b32_dpp v241, v156 row_ror:1 row_mask:0xf bank_mask:0xf
	v_fmac_f32_e32 v253, v137, v181
	v_exp_f32_e32 v189, v176
	v_mov_b32_dpp v241, v182 row_shr:1 row_mask:0xf bank_mask:0xf
	v_add_f32_e32 v165, 1.0, v189
	v_rcp_f32_e32 v186, v165
	s_nop 0
	v_mul_f32_e32 v248, v97, v186
	v_mov_b32_dpp v97, v160 row_ror:2 row_mask:0xf bank_mask:0xf
	v_mul_f32_e32 v158, v253, v248
	v_mov_b32_dpp v248, v160 row_ror:1 row_mask:0xf bank_mask:0xf
	v_mov_b32_dpp v97, v178 row_shr:2 row_mask:0xf bank_mask:0xf
	v_mov_b32_dpp v253, v156 row_ror:2 row_mask:0xf bank_mask:0xf
	v_mov_b32_dpp v248, v178 row_shr:1 row_mask:0xf bank_mask:0xf
	v_fma_f32 v154, v142, v97, v122
	v_mov_b32_dpp v253, v182 row_shr:2 row_mask:0xf bank_mask:0xf
	v_fmac_f32_e32 v154, v146, v248
	v_fma_f32 v155, v130, v253, v126
	v_fmac_f32_e32 v154, v150, v178
	v_fmac_f32_e32 v155, v134, v241
	v_mov_b32_dpp v241, v157 row_ror:1 row_mask:0xf bank_mask:0xf
	v_mul_f32_e32 v180, 0xbfb8aa3b, v154
	v_fmac_f32_e32 v155, v138, v182
	v_mov_b32_dpp v241, v183 row_shr:1 row_mask:0xf bank_mask:0xf
	v_exp_f32_e32 v153, v180
	s_nop 0
	v_add_f32_e32 v239, 1.0, v153
	v_rcp_f32_e32 v252, v239
	s_nop 0
	v_mul_f32_e32 v177, v154, v252
	v_mov_b32_dpp v154, v161 row_ror:2 row_mask:0xf bank_mask:0xf
	v_mul_f32_e32 v176, v155, v177
	v_mov_b32_dpp v177, v161 row_ror:1 row_mask:0xf bank_mask:0xf
	v_mov_b32_dpp v154, v179 row_shr:2 row_mask:0xf bank_mask:0xf
	v_mov_b32_dpp v155, v157 row_ror:2 row_mask:0xf bank_mask:0xf
	v_mov_b32_dpp v177, v179 row_shr:1 row_mask:0xf bank_mask:0xf
	v_fma_f32 v159, v143, v154, v123
	v_mov_b32_dpp v155, v183 row_shr:2 row_mask:0xf bank_mask:0xf
	v_fmac_f32_e32 v159, v147, v177
	v_fma_f32 v165, v131, v155, v127
	v_fmac_f32_e32 v159, v151, v179
	v_fmac_f32_e32 v165, v135, v241
	v_mov_b32_dpp v241, v88 row_ror:1 row_mask:0xf bank_mask:0xf
	v_mul_f32_e32 v181, 0xbfb8aa3b, v159
	v_fmac_f32_e32 v165, v139, v183
	v_mov_b32_dpp v241, v172 row_shr:1 row_mask:0xf bank_mask:0xf
	v_exp_f32_e32 v189, v181
	s_nop 0
	v_add_f32_e32 v186, 1.0, v189
	v_rcp_f32_e32 v160, v186
	s_nop 0
	v_mul_f32_e32 v156, v159, v160
	v_mov_b32_dpp v159, v92 row_ror:2 row_mask:0xf bank_mask:0xf
	v_mul_f32_e32 v248, v165, v156
	v_mov_b32_dpp v156, v92 row_ror:1 row_mask:0xf bank_mask:0xf
	v_mov_b32_dpp v159, v168 row_shr:2 row_mask:0xf bank_mask:0xf
	v_mov_b32_dpp v165, v88 row_ror:2 row_mask:0xf bank_mask:0xf
	v_mov_b32_dpp v156, v168 row_shr:1 row_mask:0xf bank_mask:0xf
	v_fma_f32 v97, v140, v159, v120
	v_mov_b32_dpp v165, v172 row_shr:2 row_mask:0xf bank_mask:0xf
	v_fmac_f32_e32 v97, v144, v156
	v_fma_f32 v253, v128, v165, v124
	v_fmac_f32_e32 v97, v148, v168
	v_fmac_f32_e32 v253, v132, v241
	v_mov_b32_dpp v241, v89 row_ror:1 row_mask:0xf bank_mask:0xf
	v_mul_f32_e32 v178, 0xbfb8aa3b, v97
	v_fmac_f32_e32 v253, v136, v172
	v_mov_b32_dpp v241, v173 row_shr:1 row_mask:0xf bank_mask:0xf
	v_exp_f32_e32 v180, v178
	s_nop 0
	v_add_f32_e32 v182, 1.0, v180
	v_rcp_f32_e32 v153, v182
	s_nop 0
	v_mul_f32_e32 v239, v97, v153
	v_mov_b32_dpp v97, v93 row_ror:2 row_mask:0xf bank_mask:0xf
	v_mul_f32_e32 v252, v253, v239
	v_mov_b32_dpp v239, v93 row_ror:1 row_mask:0xf bank_mask:0xf
	v_mov_b32_dpp v97, v169 row_shr:2 row_mask:0xf bank_mask:0xf
	v_mov_b32_dpp v253, v89 row_ror:2 row_mask:0xf bank_mask:0xf
	v_mov_b32_dpp v239, v169 row_shr:1 row_mask:0xf bank_mask:0xf
	v_fma_f32 v161, v141, v97, v121
	v_mov_b32_dpp v253, v173 row_shr:2 row_mask:0xf bank_mask:0xf
	v_fmac_f32_e32 v161, v145, v239
	v_fma_f32 v177, v129, v253, v125
	v_fmac_f32_e32 v161, v149, v169
	v_fmac_f32_e32 v177, v133, v241
	v_mov_b32_dpp v241, v90 row_ror:1 row_mask:0xf bank_mask:0xf
	v_mul_f32_e32 v157, 0xbfb8aa3b, v161
	v_fmac_f32_e32 v177, v137, v173
	v_mov_b32_dpp v241, v174 row_shr:1 row_mask:0xf bank_mask:0xf
	v_exp_f32_e32 v154, v157
	s_nop 0
	v_add_f32_e32 v179, 1.0, v154
	v_rcp_f32_e32 v181, v179
	s_nop 0
	v_mul_f32_e32 v155, v161, v181
	v_mov_b32_dpp v161, v94 row_ror:2 row_mask:0xf bank_mask:0xf
	v_mul_f32_e32 v183, v177, v155
	v_mov_b32_dpp v155, v94 row_ror:1 row_mask:0xf bank_mask:0xf
	v_mov_b32_dpp v161, v170 row_shr:2 row_mask:0xf bank_mask:0xf
	v_mov_b32_dpp v177, v90 row_ror:2 row_mask:0xf bank_mask:0xf
	v_mov_b32_dpp v155, v170 row_shr:1 row_mask:0xf bank_mask:0xf
	v_fma_f32 v189, v142, v161, v122
	v_mov_b32_dpp v177, v174 row_shr:2 row_mask:0xf bank_mask:0xf
	v_fmac_f32_e32 v189, v146, v155
	v_fma_f32 v159, v130, v177, v126
	v_fmac_f32_e32 v189, v150, v170
	v_fmac_f32_e32 v159, v134, v241
	v_mov_b32_dpp v241, v91 row_ror:1 row_mask:0xf bank_mask:0xf
	v_mul_f32_e32 v186, 0xbfb8aa3b, v189
	v_fmac_f32_e32 v159, v138, v174
	v_mov_b32_dpp v241, v175 row_shr:1 row_mask:0xf bank_mask:0xf
	v_exp_f32_e32 v160, v186
	s_nop 0
	v_add_f32_e32 v156, 1.0, v160
	v_rcp_f32_e32 v168, v156
	s_nop 0
	v_mul_f32_e32 v178, v189, v168
	v_mov_b32_dpp v189, v95 row_ror:2 row_mask:0xf bank_mask:0xf
	v_mul_f32_e32 v172, v159, v178
	v_mov_b32_dpp v178, v95 row_ror:1 row_mask:0xf bank_mask:0xf
	v_mov_b32_dpp v189, v171 row_shr:2 row_mask:0xf bank_mask:0xf
	v_mov_b32_dpp v159, v91 row_ror:2 row_mask:0xf bank_mask:0xf
	v_mov_b32_dpp v178, v171 row_shr:1 row_mask:0xf bank_mask:0xf
	v_fma_f32 v165, v143, v189, v123
	v_mov_b32_dpp v159, v175 row_shr:2 row_mask:0xf bank_mask:0xf
	v_fmac_f32_e32 v165, v147, v178
	v_fma_f32 v153, v131, v159, v127
	v_fmac_f32_e32 v165, v151, v171
	v_fmac_f32_e32 v153, v135, v241
	v_mov_b32_dpp v241, v104 row_ror:2 row_mask:0xf bank_mask:0xf
	v_mul_f32_e32 v180, 0xbfb8aa3b, v165
	v_fmac_f32_e32 v153, v139, v175
	v_mov_b32_dpp v241, v88 row_shr:2 row_mask:0xf bank_mask:0xf
	v_exp_f32_e32 v182, v180
	v_fma_f32 v161, v128, v241, v124
	v_add_f32_e32 v97, 1.0, v182
	v_rcp_f32_e32 v239, v97
	s_nop 0
	v_mul_f32_e32 v169, v165, v239
	v_mov_b32_dpp v165, v166 row_ror:2 row_mask:0xf bank_mask:0xf
	v_mul_f32_e32 v157, v153, v169
	v_mov_b32_dpp v169, v166 row_ror:1 row_mask:0xf bank_mask:0xf
	v_mov_b32_dpp v165, v92 row_shr:2 row_mask:0xf bank_mask:0xf
	s_nop 0
	v_mov_b32_dpp v169, v92 row_shr:1 row_mask:0xf bank_mask:0xf
	v_fma_f32 v253, v140, v165, v120
	v_fmac_f32_e32 v253, v144, v169
	v_mov_b32_dpp v169, v104 row_ror:1 row_mask:0xf bank_mask:0xf
	v_fmac_f32_e32 v253, v148, v92
	s_nop 0
	v_mov_b32_dpp v169, v88 row_shr:1 row_mask:0xf bank_mask:0xf
	v_mul_f32_e32 v173, 0xbfb8aa3b, v253
	v_fmac_f32_e32 v161, v132, v169
	v_mov_b32_dpp v169, v167 row_ror:2 row_mask:0xf bank_mask:0xf
	v_exp_f32_e32 v154, v173
	v_fmac_f32_e32 v161, v136, v88
	v_mov_b32_dpp v169, v93 row_shr:2 row_mask:0xf bank_mask:0xf
	v_add_f32_e32 v179, 1.0, v154
	v_fma_f32 v186, v141, v169, v121
	v_rcp_f32_e32 v181, v179
	s_nop 0
	v_mul_f32_e32 v155, v253, v181
	v_mov_b32_dpp v253, v105 row_ror:2 row_mask:0xf bank_mask:0xf
	v_mul_f32_e32 v170, v161, v155
	v_mov_b32_dpp v155, v167 row_ror:1 row_mask:0xf bank_mask:0xf
	v_mov_b32_dpp v253, v89 row_shr:2 row_mask:0xf bank_mask:0xf
	s_nop 0
	v_mov_b32_dpp v155, v93 row_shr:1 row_mask:0xf bank_mask:0xf
	v_fma_f32 v168, v129, v253, v125
	v_fmac_f32_e32 v186, v145, v155
	v_fmac_f32_e32 v186, v149, v93
	v_mov_b32_dpp v93, v105 row_ror:1 row_mask:0xf bank_mask:0xf
	v_mul_f32_e32 v177, 0xbfb8aa3b, v186
	s_nop 0
	v_mov_b32_dpp v93, v89 row_shr:1 row_mask:0xf bank_mask:0xf
	v_exp_f32_e32 v174, v177
	v_fmac_f32_e32 v168, v133, v93
	v_add_f32_e32 v160, 1.0, v174
	v_fmac_f32_e32 v168, v137, v89
	v_mov_b32_dpp v89, v106 row_ror:2 row_mask:0xf bank_mask:0xf
	v_rcp_f32_e32 v156, v160
	s_nop 0
	v_mov_b32_dpp v89, v94 row_shr:2 row_mask:0xf bank_mask:0xf
	v_mul_f32_e32 v189, v186, v156
	v_fma_f32 v171, v142, v89, v122
	v_mov_b32_dpp v186, v98 row_ror:2 row_mask:0xf bank_mask:0xf
	v_mul_f32_e32 v178, v168, v189
	v_mov_b32_dpp v189, v106 row_ror:1 row_mask:0xf bank_mask:0xf
	v_mov_b32_dpp v186, v90 row_shr:2 row_mask:0xf bank_mask:0xf
	s_nop 0
	v_mov_b32_dpp v189, v94 row_shr:1 row_mask:0xf bank_mask:0xf
	v_fma_f32 v97, v130, v186, v126
	v_fmac_f32_e32 v171, v146, v189
	v_fmac_f32_e32 v171, v150, v94
	v_mov_b32_dpp v94, v98 row_ror:1 row_mask:0xf bank_mask:0xf
	v_mul_f32_e32 v180, 0xbfb8aa3b, v171
	s_nop 0
	v_mov_b32_dpp v94, v90 row_shr:1 row_mask:0xf bank_mask:0xf
	v_exp_f32_e32 v159, v180
	v_fmac_f32_e32 v97, v134, v94
	v_add_f32_e32 v175, 1.0, v159
	v_fmac_f32_e32 v97, v138, v90
	v_mov_b32_dpp v90, v99 row_ror:1 row_mask:0xf bank_mask:0xf
	v_rcp_f32_e32 v182, v175
	s_nop 0
	v_mov_b32_dpp v90, v91 row_shr:1 row_mask:0xf bank_mask:0xf
	v_mul_f32_e32 v239, v171, v182
	v_mov_b32_dpp v171, v107 row_ror:2 row_mask:0xf bank_mask:0xf
	v_mul_f32_e32 v92, v97, v239
	v_mov_b32_dpp v239, v107 row_ror:1 row_mask:0xf bank_mask:0xf
	v_mov_b32_dpp v171, v95 row_shr:2 row_mask:0xf bank_mask:0xf
	s_nop 0
	v_mov_b32_dpp v239, v95 row_shr:1 row_mask:0xf bank_mask:0xf
	v_fma_f32 v153, v143, v171, v123
	v_fmac_f32_e32 v153, v147, v239
	v_fmac_f32_e32 v153, v151, v95
	v_mov_b32_dpp v95, v99 row_ror:2 row_mask:0xf bank_mask:0xf
	v_mul_f32_e32 v165, 0xbfb8aa3b, v153
	s_nop 0
	v_mov_b32_dpp v95, v91 row_shr:2 row_mask:0xf bank_mask:0xf
	v_exp_f32_e32 v173, v165
	v_fma_f32 v154, v131, v95, v127
	v_add_f32_e32 v179, 1.0, v173
	v_fmac_f32_e32 v154, v135, v90
	v_mov_b32_dpp v90, v100 row_ror:1 row_mask:0xf bank_mask:0xf
	v_rcp_f32_e32 v241, v179
	v_fmac_f32_e32 v154, v139, v91
	v_mov_b32_dpp v90, v104 row_shr:1 row_mask:0xf bank_mask:0xf
	v_mul_f32_e32 v88, v153, v241
	v_mov_b32_dpp v153, v112 row_ror:2 row_mask:0xf bank_mask:0xf
	v_mov_b32_dpp v91, v100 row_ror:2 row_mask:0xf bank_mask:0xf
	v_mul_f32_e32 v181, v154, v88
	v_mov_b32_dpp v88, v112 row_ror:1 row_mask:0xf bank_mask:0xf
	v_mov_b32_dpp v153, v166 row_shr:2 row_mask:0xf bank_mask:0xf
	v_mov_b32_dpp v91, v104 row_shr:2 row_mask:0xf bank_mask:0xf
	v_mov_b32_dpp v88, v166 row_shr:1 row_mask:0xf bank_mask:0xf
	v_fma_f32 v161, v140, v153, v120
	v_fma_f32 v177, v128, v91, v124
	v_fmac_f32_e32 v161, v144, v88
	v_fmac_f32_e32 v177, v132, v90
	v_mov_b32_dpp v90, v101 row_ror:1 row_mask:0xf bank_mask:0xf
	v_fmac_f32_e32 v161, v148, v166
	v_fmac_f32_e32 v177, v136, v104
	v_mov_b32_dpp v90, v105 row_shr:1 row_mask:0xf bank_mask:0xf
	v_mul_f32_e32 v169, 0xbfb8aa3b, v161
	v_exp_f32_e32 v155, v169
	s_nop 0
	v_add_f32_e32 v174, 1.0, v155
	v_mov_b32_e32 v155, 0
	v_rcp_f32_e32 v160, v174
	s_nop 0
	v_mul_f32_e32 v253, v161, v160
	v_mov_b32_dpp v161, v113 row_ror:2 row_mask:0xf bank_mask:0xf
	v_mul_f32_e32 v93, v177, v253
	v_mov_b32_dpp v253, v113 row_ror:1 row_mask:0xf bank_mask:0xf
	v_mov_b32_dpp v161, v167 row_shr:2 row_mask:0xf bank_mask:0xf
	v_mov_b32_dpp v177, v101 row_ror:2 row_mask:0xf bank_mask:0xf
	v_mov_b32_dpp v253, v167 row_shr:1 row_mask:0xf bank_mask:0xf
	v_fma_f32 v156, v141, v161, v121
	v_mov_b32_dpp v177, v105 row_shr:2 row_mask:0xf bank_mask:0xf
	v_fmac_f32_e32 v156, v145, v253
	v_fma_f32 v189, v129, v177, v125
	v_fmac_f32_e32 v156, v149, v167
	v_fmac_f32_e32 v189, v133, v90
	v_mov_b32_dpp v90, v102 row_ror:1 row_mask:0xf bank_mask:0xf
	v_mul_f32_e32 v168, 0xbfb8aa3b, v156
	v_fmac_f32_e32 v189, v137, v105
	v_mov_b32_dpp v90, v98 row_shr:1 row_mask:0xf bank_mask:0xf
	v_exp_f32_e32 v89, v168
	s_nop 0
	v_add_f32_e32 v180, 1.0, v89
	v_mov_b32_e32 v89, 0
	v_rcp_f32_e32 v159, v180
	s_nop 0
	v_mul_f32_e32 v175, v156, v159
	v_mov_b32_dpp v156, v114 row_ror:2 row_mask:0xf bank_mask:0xf
	v_mul_f32_e32 v186, v189, v175
	v_mov_b32_dpp v175, v114 row_ror:1 row_mask:0xf bank_mask:0xf
	v_mov_b32_dpp v156, v106 row_shr:2 row_mask:0xf bank_mask:0xf
	v_mov_b32_dpp v189, v102 row_ror:2 row_mask:0xf bank_mask:0xf
	v_mov_b32_dpp v175, v106 row_shr:1 row_mask:0xf bank_mask:0xf
	v_fma_f32 v94, v142, v156, v122
	v_mov_b32_dpp v189, v98 row_shr:2 row_mask:0xf bank_mask:0xf
	v_fmac_f32_e32 v94, v146, v175
	v_fma_f32 v239, v130, v189, v126
	v_fmac_f32_e32 v94, v150, v106
	v_fmac_f32_e32 v239, v134, v90
	v_mov_b32_dpp v90, v103 row_ror:1 row_mask:0xf bank_mask:0xf
	v_mul_f32_e32 v182, 0xbfb8aa3b, v94
	v_fmac_f32_e32 v239, v138, v98
	v_mov_b32_dpp v90, v99 row_shr:1 row_mask:0xf bank_mask:0xf
	v_exp_f32_e32 v171, v182
	s_nop 0
	v_add_f32_e32 v165, 1.0, v171
	v_rcp_f32_e32 v95, v165
	s_nop 0
	v_mul_f32_e32 v173, v94, v95
	v_mov_b32_dpp v94, v115 row_ror:2 row_mask:0xf bank_mask:0xf
	v_mul_f32_e32 v179, v239, v173
	v_mov_b32_dpp v173, v115 row_ror:1 row_mask:0xf bank_mask:0xf
	v_mov_b32_dpp v94, v107 row_shr:2 row_mask:0xf bank_mask:0xf
	v_mov_b32_dpp v239, v103 row_ror:2 row_mask:0xf bank_mask:0xf
	v_mov_b32_dpp v173, v107 row_shr:1 row_mask:0xf bank_mask:0xf
	v_fma_f32 v241, v143, v94, v123
	v_mov_b32_dpp v239, v99 row_shr:2 row_mask:0xf bank_mask:0xf
	v_fmac_f32_e32 v241, v147, v173
	v_fma_f32 v88, v131, v239, v127
	v_fmac_f32_e32 v241, v151, v107
	v_fmac_f32_e32 v88, v135, v90
	v_mov_b32_e32 v90, 0
	v_mul_f32_e32 v154, 0xbfb8aa3b, v241
	v_fmac_f32_e32 v88, v139, v99
	v_exp_f32_e32 v153, v154
	v_mov_b32_e32 v154, 0
	v_add_f32_e32 v166, 1.0, v153
	v_mov_b32_e32 v153, 0
	v_rcp_f32_e32 v169, v166
	s_nop 0
	v_mul_f32_e32 v91, v241, v169
	v_mul_f32_e32 v104, v88, v91
	v_mov_b32_e32 v88, 0
	v_mov_b32_e32 v91, 0
	s_and_saveexec_b64 s[58:59], s[4:5]
	s_cbranch_execz .LBB0_589
	ds_read_b128 v[152:155], v244
	ds_read_b128 v[88:91], v244 offset:512
.LBB0_589:
	s_or_b64 exec, exec, s[58:59]
	s_waitcnt lgkmcnt(1)
	v_mov_b32_dpp v97, v152 row_ror:1 row_mask:0xf bank_mask:0xf
	v_mov_b32_dpp v163, v152 row_ror:2 row_mask:0xf bank_mask:0xf
	v_mov_b32_e32 v106, v240
	v_mov_b32_dpp v97, v112 row_shr:1 row_mask:0xf bank_mask:0xf
	v_mov_b32_dpp v163, v112 row_shr:2 row_mask:0xf bank_mask:0xf
	v_fma_f32 v174, v140, v163, v120
	v_fmac_f32_e32 v174, v144, v97
	v_fmac_f32_e32 v174, v148, v112
	v_mul_f32_e32 v160, 0xbfb8aa3b, v174
	v_exp_f32_e32 v161, v160
	s_waitcnt lgkmcnt(0)
	v_mov_b32_dpp v112, v88 row_ror:1 row_mask:0xf bank_mask:0xf
	v_mov_b32_dpp v140, v88 row_ror:2 row_mask:0xf bank_mask:0xf
	v_mov_b32_e32 v107, v240
	v_mov_b32_dpp v112, v100 row_shr:1 row_mask:0xf bank_mask:0xf
	v_mov_b32_dpp v140, v100 row_shr:2 row_mask:0xf bank_mask:0xf
	v_add_f32_e32 v253, 1.0, v161
	v_pk_mul_f32 v[70:71], v[70:71], v[106:107]
	v_fma_f32 v168, v128, v140, v124
	v_rcp_f32_e32 v167, v253
	v_fmac_f32_e32 v168, v132, v112
	v_mov_b32_dpp v112, v89 row_ror:1 row_mask:0xf bank_mask:0xf
	v_mul_f32_e32 v177, v174, v167
	v_fmac_f32_e32 v168, v136, v100
	v_mov_b32_dpp v100, v153 row_ror:2 row_mask:0xf bank_mask:0xf
	v_mov_b32_dpp v112, v101 row_shr:1 row_mask:0xf bank_mask:0xf
	v_mul_f32_e32 v105, v168, v177
	v_mov_b32_dpp v168, v153 row_ror:1 row_mask:0xf bank_mask:0xf
	v_mov_b32_dpp v100, v113 row_shr:2 row_mask:0xf bank_mask:0xf
	v_pk_mul_f32 v[66:67], v[66:67], v[106:107]
	v_mov_b32_dpp v168, v113 row_shr:1 row_mask:0xf bank_mask:0xf
	v_fma_f32 v180, v141, v100, v121
	v_mov_b32_e32 v106, v238
	v_mov_b32_e32 v107, v238
	v_fmac_f32_e32 v180, v145, v168
	v_mov_b32_e32 v241, v240
	v_pk_mul_f32 v[62:63], v[62:63], v[106:107]
	v_fmac_f32_e32 v180, v149, v113
	v_mov_b32_dpp v113, v89 row_ror:2 row_mask:0xf bank_mask:0xf
	v_pk_mul_f32 v[58:59], v[58:59], v[106:107]
	v_mul_f32_e32 v159, 0xbfb8aa3b, v180
	v_mov_b32_dpp v113, v101 row_shr:2 row_mask:0xf bank_mask:0xf
	v_mov_b32_dpp v106, v90 row_ror:2 row_mask:0xf bank_mask:0xf
	v_exp_f32_e32 v156, v159
	v_fma_f32 v189, v129, v113, v125
	v_mov_b32_dpp v106, v102 row_shr:2 row_mask:0xf bank_mask:0xf
	v_add_f32_e32 v175, 1.0, v156
	v_fmac_f32_e32 v189, v133, v112
	v_fma_f32 v99, v130, v106, v126
	v_rcp_f32_e32 v182, v175
	v_fmac_f32_e32 v189, v137, v101
	v_mov_b32_dpp v101, v90 row_ror:1 row_mask:0xf bank_mask:0xf
	v_mul_f32_e32 v98, v180, v182
	v_mov_b32_dpp v180, v154 row_ror:2 row_mask:0xf bank_mask:0xf
	v_mov_b32_dpp v101, v102 row_shr:1 row_mask:0xf bank_mask:0xf
	v_mul_f32_e32 v171, v189, v98
	v_mov_b32_dpp v189, v154 row_ror:1 row_mask:0xf bank_mask:0xf
	v_mov_b32_dpp v180, v114 row_shr:2 row_mask:0xf bank_mask:0xf
	v_fmac_f32_e32 v99, v134, v101
	v_mov_b32_dpp v189, v114 row_shr:1 row_mask:0xf bank_mask:0xf
	v_fma_f32 v165, v142, v180, v122
	v_fmac_f32_e32 v99, v138, v102
	v_mov_b32_dpp v101, v91 row_ror:2 row_mask:0xf bank_mask:0xf
	v_fmac_f32_e32 v165, v146, v189
	v_pk_mul_f32 v[68:69], v[68:69], v[240:241]
	v_mov_b32_dpp v101, v103 row_shr:2 row_mask:0xf bank_mask:0xf
	v_fmac_f32_e32 v165, v150, v114
	v_pk_mul_f32 v[64:65], v[64:65], v[240:241]
	v_fmac_f32_e32 v127, v131, v101
	v_mul_f32_e32 v95, 0xbfb8aa3b, v165
	v_exp_f32_e32 v94, v95
	s_nop 0
	v_add_f32_e32 v173, 1.0, v94
	v_rcp_f32_e32 v239, v173
	s_nop 0
	v_mul_f32_e32 v166, v165, v239
	v_mov_b32_dpp v165, v155 row_ror:2 row_mask:0xf bank_mask:0xf
	v_mov_b32_e32 v239, v238
	v_mul_f32_e32 v169, v99, v166
	v_mov_b32_dpp v99, v155 row_ror:1 row_mask:0xf bank_mask:0xf
	v_mov_b32_dpp v165, v115 row_shr:2 row_mask:0xf bank_mask:0xf
	v_pk_mul_f32 v[60:61], v[60:61], v[238:239]
	v_mov_b32_dpp v99, v115 row_shr:1 row_mask:0xf bank_mask:0xf
	v_fmac_f32_e32 v123, v143, v165
	v_mov_b32_dpp v165, v91 row_ror:1 row_mask:0xf bank_mask:0xf
	v_pk_mul_f32 v[56:57], v[56:57], v[238:239]
	v_fmac_f32_e32 v123, v147, v99
	v_mov_b32_dpp v165, v103 row_shr:1 row_mask:0xf bank_mask:0xf
	v_mov_b32_dpp v101, v56 row_ror:1 row_mask:0xf bank_mask:0xf
	v_fmac_f32_e32 v123, v151, v115
	v_fmac_f32_e32 v127, v135, v165
	v_mov_b32_dpp v165, v60 row_ror:2 row_mask:0xf bank_mask:0xf
	v_mul_f32_e32 v152, 0xbfb8aa3b, v123
	v_fmac_f32_e32 v127, v139, v103
	v_mov_b32_dpp v165, v108 row_shr:2 row_mask:0xf bank_mask:0xf
	v_exp_f32_e32 v120, v152
	v_mov_b32_dpp v101, v116 row_shr:1 row_mask:0xf bank_mask:0xf
	v_mov_b32_dpp v102, v56 row_ror:2 row_mask:0xf bank_mask:0xf
	v_add_f32_e32 v163, 1.0, v120
	v_mov_b32_dpp v120, v60 row_ror:1 row_mask:0xf bank_mask:0xf
	v_mov_b32_dpp v102, v116 row_shr:2 row_mask:0xf bank_mask:0xf
	v_rcp_f32_e32 v97, v163
	v_mov_b32_dpp v120, v108 row_shr:1 row_mask:0xf bank_mask:0xf
	v_mul_f32_e32 v144, v123, v97
	v_mul_f32_e32 v148, v127, v144
	s_waitcnt vmcnt(5)
	v_fma_f32 v160, v28, v165, v24
	s_waitcnt vmcnt(3)
	v_fmac_f32_e32 v160, v36, v120
	s_waitcnt vmcnt(1)
	v_fmac_f32_e32 v160, v108, v44
	v_fma_f32 v253, v40, v102, v32
	v_mul_f32_e32 v88, 0xbfb8aa3b, v160
	v_fmac_f32_e32 v253, v48, v101
	v_exp_f32_e32 v161, v88
	s_waitcnt vmcnt(0)
	v_fmac_f32_e32 v253, v116, v52
	v_add_f32_e32 v124, 1.0, v161
	v_mov_b32_dpp v101, v61 row_ror:2 row_mask:0xf bank_mask:0xf
	v_mov_b32_dpp v103, v57 row_ror:2 row_mask:0xf bank_mask:0xf
	v_rcp_f32_e32 v128, v124
	v_mov_b32_dpp v101, v109 row_shr:2 row_mask:0xf bank_mask:0xf
	v_mov_b32_dpp v103, v117 row_shr:2 row_mask:0xf bank_mask:0xf
	v_mul_f32_e32 v140, v160, v128
	v_fma_f32 v136, v29, v101, v25
	v_fma_f32 v177, v41, v103, v33
	v_mul_f32_e32 v132, v253, v140
	v_mov_b32_dpp v140, v61 row_ror:1 row_mask:0xf bank_mask:0xf
	v_mov_b32_dpp v253, v57 row_ror:1 row_mask:0xf bank_mask:0xf
	v_mov_b32_dpp v106, v58 row_ror:2 row_mask:0xf bank_mask:0xf
	v_mov_b32_dpp v140, v109 row_shr:1 row_mask:0xf bank_mask:0xf
	v_mov_b32_dpp v253, v117 row_shr:1 row_mask:0xf bank_mask:0xf
	v_mov_b32_dpp v106, v118 row_shr:2 row_mask:0xf bank_mask:0xf
	v_fmac_f32_e32 v136, v37, v140
	v_fmac_f32_e32 v177, v49, v253
	v_mov_b32_dpp v253, v62 row_ror:2 row_mask:0xf bank_mask:0xf
	v_fmac_f32_e32 v136, v109, v45
	v_fmac_f32_e32 v177, v117, v53
	v_mov_b32_dpp v253, v110 row_shr:2 row_mask:0xf bank_mask:0xf
	v_mul_f32_e32 v167, 0xbfb8aa3b, v136
	v_fma_f32 v159, v42, v106, v34
	v_fma_f32 v145, v30, v253, v26
	v_exp_f32_e32 v174, v167
	v_mov_b32_dpp v107, v59 row_ror:2 row_mask:0xf bank_mask:0xf
	v_add_f32_e32 v153, 1.0, v174
	s_nop 0
	v_mov_b32_dpp v107, v119 row_shr:2 row_mask:0xf bank_mask:0xf
	v_rcp_f32_e32 v100, v153
	v_fma_f32 v133, v43, v107, v35
	v_mul_f32_e32 v121, v136, v100
	v_mul_f32_e32 v141, v177, v121
	s_nop 0
	v_mov_b32_dpp v121, v62 row_ror:1 row_mask:0xf bank_mask:0xf
	v_mov_b32_dpp v177, v58 row_ror:1 row_mask:0xf bank_mask:0xf
	s_nop 0
	v_mov_b32_dpp v121, v110 row_shr:1 row_mask:0xf bank_mask:0xf
	v_mov_b32_dpp v177, v118 row_shr:1 row_mask:0xf bank_mask:0xf
	v_fmac_f32_e32 v145, v38, v121
	v_fmac_f32_e32 v159, v50, v177
	v_mov_b32_dpp v177, v63 row_ror:2 row_mask:0xf bank_mask:0xf
	v_fmac_f32_e32 v145, v110, v46
	v_fmac_f32_e32 v159, v118, v54
	v_mov_b32_dpp v177, v111 row_shr:2 row_mask:0xf bank_mask:0xf
	v_mul_f32_e32 v168, 0xbfb8aa3b, v145
	v_fma_f32 v125, v31, v177, v27
	v_exp_f32_e32 v149, v168
	s_nop 0
	v_add_f32_e32 v89, 1.0, v149
	v_rcp_f32_e32 v156, v89
	s_nop 0
	v_mul_f32_e32 v175, v145, v156
	v_mul_f32_e32 v113, v159, v175
	s_nop 0
	v_mov_b32_dpp v175, v63 row_ror:1 row_mask:0xf bank_mask:0xf
	v_mov_b32_dpp v159, v59 row_ror:1 row_mask:0xf bank_mask:0xf
	s_nop 0
	v_mov_b32_dpp v175, v111 row_shr:1 row_mask:0xf bank_mask:0xf
	v_mov_b32_dpp v159, v119 row_shr:1 row_mask:0xf bank_mask:0xf
	v_fmac_f32_e32 v125, v39, v175
	v_fmac_f32_e32 v133, v51, v159
	v_mov_b32_dpp v159, v68 row_ror:2 row_mask:0xf bank_mask:0xf
	v_fmac_f32_e32 v125, v111, v47
	v_fmac_f32_e32 v133, v119, v55
	v_mov_b32_dpp v159, v60 row_shr:2 row_mask:0xf bank_mask:0xf
	v_mul_f32_e32 v129, 0xbfb8aa3b, v125
	v_fma_f32 v122, v28, v159, v24
	v_exp_f32_e32 v112, v129
	s_nop 0
	v_add_f32_e32 v137, 1.0, v112
	v_rcp_f32_e32 v182, v137
	s_nop 0
	v_mul_f32_e32 v98, v125, v182
	v_mul_f32_e32 v154, v133, v98
	s_nop 0
	v_mov_b32_dpp v98, v68 row_ror:1 row_mask:0xf bank_mask:0xf
	v_mov_b32_dpp v133, v64 row_ror:2 row_mask:0xf bank_mask:0xf
	s_nop 0
	v_mov_b32_dpp v98, v60 row_shr:1 row_mask:0xf bank_mask:0xf
	v_mov_b32_dpp v133, v56 row_shr:2 row_mask:0xf bank_mask:0xf
	v_fmac_f32_e32 v122, v36, v98
	v_mov_b32_dpp v98, v64 row_ror:1 row_mask:0xf bank_mask:0xf
	v_fma_f32 v114, v40, v133, v32
	v_fmac_f32_e32 v122, v60, v44
	v_mov_b32_dpp v98, v56 row_shr:1 row_mask:0xf bank_mask:0xf
	v_mov_b32_e32 v60, 0
	v_mul_f32_e32 v142, 0xbfb8aa3b, v122
	v_fmac_f32_e32 v114, v48, v98
	v_mov_b32_dpp v98, v65 row_ror:2 row_mask:0xf bank_mask:0xf
	v_exp_f32_e32 v180, v142
	v_fmac_f32_e32 v114, v56, v52
	v_mov_b32_dpp v98, v57 row_shr:2 row_mask:0xf bank_mask:0xf
	v_add_f32_e32 v146, 1.0, v180
	v_mov_b32_e32 v56, 0
	v_fma_f32 v134, v41, v98, v33
	v_rcp_f32_e32 v189, v146
	s_nop 0
	v_mul_f32_e32 v150, v122, v189
	v_mov_b32_dpp v189, v69 row_ror:2 row_mask:0xf bank_mask:0xf
	v_mul_f32_e32 v95, v114, v150
	v_mov_b32_dpp v150, v69 row_ror:1 row_mask:0xf bank_mask:0xf
	v_mov_b32_dpp v189, v61 row_shr:2 row_mask:0xf bank_mask:0xf
	s_nop 0
	v_mov_b32_dpp v150, v61 row_shr:1 row_mask:0xf bank_mask:0xf
	v_fma_f32 v90, v29, v189, v25
	v_fmac_f32_e32 v90, v37, v150
	v_fmac_f32_e32 v90, v61, v45
	v_mov_b32_dpp v61, v65 row_ror:1 row_mask:0xf bank_mask:0xf
	v_mul_f32_e32 v94, 0xbfb8aa3b, v90
	s_nop 0
	v_mov_b32_dpp v61, v57 row_shr:1 row_mask:0xf bank_mask:0xf
	v_exp_f32_e32 v173, v94
	v_fmac_f32_e32 v134, v49, v61
	v_mov_b32_dpp v61, v66 row_ror:2 row_mask:0xf bank_mask:0xf
	v_add_f32_e32 v126, 1.0, v173
	v_fmac_f32_e32 v134, v57, v53
	v_mov_b32_dpp v57, v70 row_ror:2 row_mask:0xf bank_mask:0xf
	v_rcp_f32_e32 v130, v126
	s_nop 0
	v_mov_b32_dpp v57, v62 row_shr:2 row_mask:0xf bank_mask:0xf
	v_mov_b32_dpp v61, v58 row_shr:2 row_mask:0xf bank_mask:0xf
	v_mul_f32_e32 v138, v90, v130
	v_mov_b32_dpp v90, v66 row_ror:1 row_mask:0xf bank_mask:0xf
	v_fma_f32 v155, v30, v57, v26
	v_mul_f32_e32 v166, v134, v138
	v_mov_b32_dpp v138, v70 row_ror:1 row_mask:0xf bank_mask:0xf
	v_mov_b32_dpp v90, v58 row_shr:1 row_mask:0xf bank_mask:0xf
	v_fma_f32 v147, v42, v61, v34
	v_mov_b32_dpp v138, v62 row_shr:1 row_mask:0xf bank_mask:0xf
	v_mov_b32_e32 v61, 0
	v_fmac_f32_e32 v147, v50, v90
	v_fmac_f32_e32 v155, v38, v138
	v_mov_b32_dpp v90, v67 row_ror:2 row_mask:0xf bank_mask:0xf
	v_fmac_f32_e32 v147, v58, v54
	v_fmac_f32_e32 v155, v62, v46
	v_mov_b32_dpp v58, v67 row_ror:1 row_mask:0xf bank_mask:0xf
	v_mov_b32_dpp v90, v59 row_shr:2 row_mask:0xf bank_mask:0xf
	v_mul_f32_e32 v143, 0xbfb8aa3b, v155
	v_mov_b32_dpp v58, v59 row_shr:1 row_mask:0xf bank_mask:0xf
	v_fma_f32 v139, v43, v90, v35
	v_exp_f32_e32 v99, v143
	v_fmac_f32_e32 v139, v51, v58
	v_mov_b32_dpp v58, v84 row_ror:1 row_mask:0xf bank_mask:0xf
	v_add_f32_e32 v115, 1.0, v99
	v_fmac_f32_e32 v139, v59, v55
	v_mov_b32_dpp v58, v64 row_shr:1 row_mask:0xf bank_mask:0xf
	v_rcp_f32_e32 v151, v115
	v_mov_b32_dpp v59, v84 row_ror:2 row_mask:0xf bank_mask:0xf
	v_mov_b32_e32 v62, 0
	v_mul_f32_e32 v152, v155, v151
	v_mov_b32_dpp v155, v71 row_ror:2 row_mask:0xf bank_mask:0xf
	v_mov_b32_dpp v59, v64 row_shr:2 row_mask:0xf bank_mask:0xf
	v_mul_f32_e32 v91, v147, v152
	v_mov_b32_dpp v152, v71 row_ror:1 row_mask:0xf bank_mask:0xf
	v_mov_b32_dpp v155, v63 row_shr:2 row_mask:0xf bank_mask:0xf
	v_fma_f32 v88, v40, v59, v32
	v_mov_b32_dpp v152, v63 row_shr:1 row_mask:0xf bank_mask:0xf
	v_fma_f32 v163, v31, v155, v27
	v_fmac_f32_e32 v88, v48, v58
	v_mov_b32_dpp v58, v85 row_ror:1 row_mask:0xf bank_mask:0xf
	v_fmac_f32_e32 v163, v39, v152
	v_fmac_f32_e32 v88, v64, v52
	v_mov_b32_dpp v58, v65 row_shr:1 row_mask:0xf bank_mask:0xf
	v_fmac_f32_e32 v163, v63, v47
	v_mov_b32_e32 v63, 0
	v_mov_b32_e32 v64, 0
	v_mul_f32_e32 v131, 0xbfb8aa3b, v163
	v_mov_b32_e32 v59, 0
	v_exp_f32_e32 v135, v131
	s_nop 0
	v_add_f32_e32 v97, 1.0, v135
	v_rcp_f32_e32 v123, v97
	s_nop 0
	v_mul_f32_e32 v127, v163, v123
	v_mov_b32_dpp v163, v80 row_ror:2 row_mask:0xf bank_mask:0xf
	v_mul_f32_e32 v144, v139, v127
	v_mov_b32_dpp v127, v80 row_ror:1 row_mask:0xf bank_mask:0xf
	v_mov_b32_dpp v163, v68 row_shr:2 row_mask:0xf bank_mask:0xf
	s_nop 0
	v_mov_b32_dpp v127, v68 row_shr:1 row_mask:0xf bank_mask:0xf
	v_fma_f32 v165, v28, v163, v24
	v_fmac_f32_e32 v165, v36, v127
	v_fmac_f32_e32 v165, v68, v44
	v_mul_f32_e32 v120, 0xbfb8aa3b, v165
	v_exp_f32_e32 v108, v120
	s_nop 0
	v_add_f32_e32 v102, 1.0, v108
	v_rcp_f32_e32 v116, v102
	s_nop 0
	v_mul_f32_e32 v161, v165, v116
	v_mov_b32_dpp v165, v81 row_ror:2 row_mask:0xf bank_mask:0xf
	v_mul_f32_e32 v124, v88, v161
	v_mov_b32_dpp v161, v81 row_ror:1 row_mask:0xf bank_mask:0xf
	v_mov_b32_dpp v165, v69 row_shr:2 row_mask:0xf bank_mask:0xf
	v_mov_b32_dpp v88, v85 row_ror:2 row_mask:0xf bank_mask:0xf
	v_mov_b32_dpp v161, v69 row_shr:1 row_mask:0xf bank_mask:0xf
	v_fma_f32 v128, v29, v165, v25
	v_mov_b32_dpp v88, v65 row_shr:2 row_mask:0xf bank_mask:0xf
	v_fmac_f32_e32 v128, v37, v161
	v_fma_f32 v140, v41, v88, v33
	v_fmac_f32_e32 v128, v69, v45
	v_fmac_f32_e32 v140, v49, v58
	v_mov_b32_dpp v58, v86 row_ror:1 row_mask:0xf bank_mask:0xf
	v_mul_f32_e32 v160, 0xbfb8aa3b, v128
	v_fmac_f32_e32 v140, v65, v53
	v_mov_b32_dpp v58, v66 row_shr:1 row_mask:0xf bank_mask:0xf
	v_exp_f32_e32 v101, v160
	v_mov_b32_e32 v65, 0
	v_add_f32_e32 v109, 1.0, v101
	v_rcp_f32_e32 v167, v109
	s_nop 0
	v_mul_f32_e32 v103, v128, v167
	v_mov_b32_dpp v128, v82 row_ror:2 row_mask:0xf bank_mask:0xf
	v_mul_f32_e32 v117, v140, v103
	v_mov_b32_dpp v103, v82 row_ror:1 row_mask:0xf bank_mask:0xf
	v_mov_b32_dpp v128, v70 row_shr:2 row_mask:0xf bank_mask:0xf
	v_mov_b32_dpp v140, v86 row_ror:2 row_mask:0xf bank_mask:0xf
	v_mov_b32_dpp v103, v70 row_shr:1 row_mask:0xf bank_mask:0xf
	v_fma_f32 v174, v30, v128, v26
	v_mov_b32_dpp v140, v66 row_shr:2 row_mask:0xf bank_mask:0xf
	v_fmac_f32_e32 v174, v38, v103
	v_fma_f32 v136, v42, v140, v34
	v_fmac_f32_e32 v174, v70, v46
	v_fmac_f32_e32 v136, v50, v58
	v_mov_b32_dpp v58, v87 row_ror:1 row_mask:0xf bank_mask:0xf
	v_mul_f32_e32 v153, 0xbfb8aa3b, v174
	v_fmac_f32_e32 v136, v66, v54
	v_mov_b32_dpp v58, v67 row_shr:1 row_mask:0xf bank_mask:0xf
	v_exp_f32_e32 v100, v153
	s_nop 0
	v_add_f32_e32 v253, 1.0, v100
	v_rcp_f32_e32 v121, v253
	s_nop 0
	v_mul_f32_e32 v168, v174, v121
	v_mov_b32_dpp v174, v83 row_ror:2 row_mask:0xf bank_mask:0xf
	v_mul_f32_e32 v106, v136, v168
	v_mov_b32_dpp v168, v83 row_ror:1 row_mask:0xf bank_mask:0xf
	v_mov_b32_dpp v174, v71 row_shr:2 row_mask:0xf bank_mask:0xf
	v_mov_b32_dpp v136, v87 row_ror:2 row_mask:0xf bank_mask:0xf
	v_mov_b32_dpp v168, v71 row_shr:1 row_mask:0xf bank_mask:0xf
	v_fma_f32 v118, v31, v174, v27
	v_mov_b32_dpp v136, v67 row_shr:2 row_mask:0xf bank_mask:0xf
	v_fmac_f32_e32 v118, v39, v168
	v_fma_f32 v145, v43, v136, v35
	v_fmac_f32_e32 v118, v71, v47
	v_fmac_f32_e32 v145, v51, v58
	v_mov_b32_e32 v58, 0
	v_mul_f32_e32 v149, 0xbfb8aa3b, v118
	v_fmac_f32_e32 v145, v67, v55
	v_exp_f32_e32 v89, v149
	s_nop 0
	v_add_f32_e32 v156, 1.0, v89
	v_rcp_f32_e32 v177, v156
	s_nop 0
	v_mul_f32_e32 v175, v118, v177
	v_mul_f32_e32 v111, v145, v175
	s_and_saveexec_b64 s[58:59], s[36:37]
	s_cbranch_execz .LBB0_591
	ds_read_b128 v[62:65], v207 offset:16
	ds_read_b128 v[58:61], v207 offset:528
.LBB0_591:
	s_or_b64 exec, exec, s[58:59]
	s_waitcnt lgkmcnt(1)
	v_mov_b32_dpp v118, v62 row_ror:1 row_mask:0xf bank_mask:0xf
	v_mov_b32_dpp v110, v62 row_ror:2 row_mask:0xf bank_mask:0xf
	v_mov_b32_e32 v70, v164
	v_mov_b32_dpp v118, v80 row_shr:1 row_mask:0xf bank_mask:0xf
	v_mov_b32_dpp v110, v80 row_shr:2 row_mask:0xf bank_mask:0xf
	v_fma_f32 v129, v28, v110, v24
	v_fmac_f32_e32 v129, v36, v118
	v_fmac_f32_e32 v129, v80, v44
	v_mul_f32_e32 v107, 0xbfb8aa3b, v129
	v_exp_f32_e32 v119, v107
	s_waitcnt lgkmcnt(0)
	v_mov_b32_dpp v80, v58 row_ror:1 row_mask:0xf bank_mask:0xf
	v_mov_b32_dpp v110, v58 row_ror:2 row_mask:0xf bank_mask:0xf
	v_mov_b32_e32 v71, v164
	v_mov_b32_dpp v80, v84 row_shr:1 row_mask:0xf bank_mask:0xf
	v_mov_b32_dpp v110, v84 row_shr:2 row_mask:0xf bank_mask:0xf
	v_add_f32_e32 v112, 1.0, v119
	v_pk_mul_f32 v[22:23], v[22:23], v[70:71]
	v_fma_f32 v125, v40, v110, v32
	v_rcp_f32_e32 v137, v112
	v_fmac_f32_e32 v125, v48, v80
	v_mov_b32_dpp v80, v59 row_ror:2 row_mask:0xf bank_mask:0xf
	v_mul_f32_e32 v182, v129, v137
	v_fmac_f32_e32 v125, v84, v52
	v_mov_b32_dpp v80, v85 row_shr:2 row_mask:0xf bank_mask:0xf
	v_pk_mul_f32 v[14:15], v[14:15], v[70:71]
	v_mul_f32_e32 v159, v125, v182
	v_mov_b32_dpp v182, v63 row_ror:1 row_mask:0xf bank_mask:0xf
	v_mov_b32_dpp v125, v63 row_ror:2 row_mask:0xf bank_mask:0xf
	v_mov_b32_dpp v63, v59 row_ror:1 row_mask:0xf bank_mask:0xf
	v_mov_b32_dpp v182, v81 row_shr:1 row_mask:0xf bank_mask:0xf
	v_mov_b32_dpp v125, v81 row_shr:2 row_mask:0xf bank_mask:0xf
	v_mov_b32_dpp v63, v85 row_shr:1 row_mask:0xf bank_mask:0xf
	v_fma_f32 v133, v41, v80, v33
	v_fma_f32 v142, v29, v125, v25
	v_mov_b32_e32 v70, v162
	v_fmac_f32_e32 v133, v49, v63
	v_fmac_f32_e32 v142, v37, v182
	v_mov_b32_e32 v71, v162
	v_fmac_f32_e32 v133, v85, v53
	v_fmac_f32_e32 v142, v81, v45
	v_mov_b32_e32 v165, v164
	v_mov_b32_e32 v163, v162
	v_mul_f32_e32 v180, 0xbfb8aa3b, v142
	v_mov_b32_e32 v97, v96
	v_pk_mul_f32 v[18:19], v[18:19], v[70:71]
	v_exp_f32_e32 v146, v180
	v_pk_mul_f32 v[10:11], v[10:11], v[70:71]
	v_mov_b32_e32 v70, v96
	v_add_f32_e32 v122, 1.0, v146
	v_mov_b32_e32 v71, v96
	v_pk_mul_f32 v[20:21], v[20:21], v[164:165]
	v_rcp_f32_e32 v114, v122
	v_pk_mul_f32 v[12:13], v[12:13], v[164:165]
	v_pk_mul_f32 v[8:9], v[8:9], v[162:163]
	v_mul_f32_e32 v189, v142, v114
	v_mov_b32_dpp v142, v64 row_ror:2 row_mask:0xf bank_mask:0xf
	v_pk_mul_f32 v[6:7], v[6:7], v[70:71]
	v_mul_f32_e32 v150, v133, v189
	v_mov_b32_dpp v189, v64 row_ror:1 row_mask:0xf bank_mask:0xf
	v_mov_b32_dpp v142, v82 row_shr:2 row_mask:0xf bank_mask:0xf
	v_mov_b32_dpp v133, v60 row_ror:1 row_mask:0xf bank_mask:0xf
	v_mov_b32_dpp v189, v82 row_shr:1 row_mask:0xf bank_mask:0xf
	v_mov_b32_dpp v64, v60 row_ror:2 row_mask:0xf bank_mask:0xf
	v_mov_b32_dpp v133, v86 row_shr:1 row_mask:0xf bank_mask:0xf
	v_fma_f32 v94, v30, v142, v26
	v_mov_b32_dpp v64, v86 row_shr:2 row_mask:0xf bank_mask:0xf
	v_pk_mul_f32 v[4:5], v[4:5], v[96:97]
	v_fmac_f32_e32 v94, v38, v189
	v_fma_f32 v98, v42, v64, v34
	v_pk_mul_f32 v[2:3], v[2:3], v[70:71]
	v_fmac_f32_e32 v94, v82, v46
	v_fmac_f32_e32 v98, v50, v133
	v_mov_b32_dpp v133, v61 row_ror:1 row_mask:0xf bank_mask:0xf
	v_mul_f32_e32 v173, 0xbfb8aa3b, v94
	v_fmac_f32_e32 v98, v86, v54
	v_mov_b32_dpp v133, v87 row_shr:1 row_mask:0xf bank_mask:0xf
	v_exp_f32_e32 v126, v173
	v_pk_mul_f32 v[0:1], v[0:1], v[96:97]
	v_pk_mul_f32 v[16:17], v[16:17], v[162:163]
	v_add_f32_e32 v130, 1.0, v126
	v_mov_b32_dpp v70, v2 row_ror:2 row_mask:0xf bank_mask:0xf
	v_mov_b32_dpp v71, v3 row_ror:2 row_mask:0xf bank_mask:0xf
	v_rcp_f32_e32 v134, v130
	v_mov_b32_dpp v70, v78 row_shr:2 row_mask:0xf bank_mask:0xf
	v_mov_b32_dpp v71, v79 row_shr:2 row_mask:0xf bank_mask:0xf
	v_mul_f32_e32 v57, v94, v134
	v_mov_b32_dpp v94, v65 row_ror:2 row_mask:0xf bank_mask:0xf
	v_fma_f32 v153, v42, v70, v34
	v_mul_f32_e32 v138, v98, v57
	v_mov_b32_dpp v57, v65 row_ror:1 row_mask:0xf bank_mask:0xf
	v_mov_b32_dpp v94, v83 row_shr:2 row_mask:0xf bank_mask:0xf
	v_mov_b32_dpp v98, v61 row_ror:2 row_mask:0xf bank_mask:0xf
	v_mov_b32_dpp v57, v83 row_shr:1 row_mask:0xf bank_mask:0xf
	v_fma_f32 v143, v31, v94, v27
	v_mov_b32_dpp v98, v87 row_shr:2 row_mask:0xf bank_mask:0xf
	v_mov_b32_dpp v61, v1 row_ror:2 row_mask:0xf bank_mask:0xf
	v_fmac_f32_e32 v143, v39, v57
	v_fma_f32 v151, v43, v98, v35
	v_mov_b32_dpp v61, v77 row_shr:2 row_mask:0xf bank_mask:0xf
	v_fmac_f32_e32 v143, v83, v47
	v_fmac_f32_e32 v151, v51, v133
	v_mov_b32_dpp v133, v0 row_ror:1 row_mask:0xf bank_mask:0xf
	v_mul_f32_e32 v99, 0xbfb8aa3b, v143
	v_fmac_f32_e32 v151, v87, v55
	v_mov_b32_dpp v133, v76 row_shr:1 row_mask:0xf bank_mask:0xf
	v_exp_f32_e32 v115, v99
	v_fma_f32 v69, v41, v61, v33
	v_fma_f32 v149, v43, v71, v35
	v_add_f32_e32 v147, 1.0, v115
	v_rcp_f32_e32 v155, v147
	s_nop 0
	v_mul_f32_e32 v152, v143, v155
	v_mov_b32_dpp v143, v4 row_ror:2 row_mask:0xf bank_mask:0xf
	v_mul_f32_e32 v131, v151, v152
	v_mov_b32_dpp v152, v4 row_ror:1 row_mask:0xf bank_mask:0xf
	v_mov_b32_dpp v143, v72 row_shr:2 row_mask:0xf bank_mask:0xf
	v_mov_b32_dpp v151, v0 row_ror:2 row_mask:0xf bank_mask:0xf
	v_mov_b32_dpp v152, v72 row_shr:1 row_mask:0xf bank_mask:0xf
	v_fma_f32 v90, v28, v143, v24
	v_mov_b32_dpp v151, v76 row_shr:2 row_mask:0xf bank_mask:0xf
	v_fmac_f32_e32 v90, v36, v152
	v_fma_f32 v139, v40, v151, v32
	v_fmac_f32_e32 v90, v72, v44
	v_fmac_f32_e32 v139, v48, v133
	v_mov_b32_dpp v133, v1 row_ror:1 row_mask:0xf bank_mask:0xf
	v_mul_f32_e32 v135, 0xbfb8aa3b, v90
	v_fmac_f32_e32 v139, v76, v52
	v_mov_b32_dpp v133, v77 row_shr:1 row_mask:0xf bank_mask:0xf
	v_exp_f32_e32 v123, v135
	v_fmac_f32_e32 v69, v49, v133
	v_mov_b32_dpp v133, v2 row_ror:1 row_mask:0xf bank_mask:0xf
	v_add_f32_e32 v127, 1.0, v123
	v_fmac_f32_e32 v69, v77, v53
	v_mov_b32_dpp v133, v78 row_shr:1 row_mask:0xf bank_mask:0xf
	v_rcp_f32_e32 v68, v127
	v_fmac_f32_e32 v153, v50, v133
	v_mov_b32_dpp v133, v3 row_ror:1 row_mask:0xf bank_mask:0xf
	v_mul_f32_e32 v120, v90, v68
	v_mov_b32_dpp v90, v5 row_ror:2 row_mask:0xf bank_mask:0xf
	v_fmac_f32_e32 v153, v78, v54
	v_mul_f32_e32 v108, v139, v120
	v_mov_b32_dpp v120, v5 row_ror:1 row_mask:0xf bank_mask:0xf
	v_mov_b32_dpp v90, v73 row_shr:2 row_mask:0xf bank_mask:0xf
	v_mov_b32_dpp v133, v79 row_shr:1 row_mask:0xf bank_mask:0xf
	v_mov_b32_dpp v120, v73 row_shr:1 row_mask:0xf bank_mask:0xf
	v_fma_f32 v102, v29, v90, v25
	v_fmac_f32_e32 v149, v51, v133
	v_mov_b32_dpp v133, v8 row_ror:2 row_mask:0xf bank_mask:0xf
	v_fmac_f32_e32 v102, v37, v120
	v_fmac_f32_e32 v149, v79, v55
	v_mov_b32_dpp v133, v0 row_shr:2 row_mask:0xf bank_mask:0xf
	v_fmac_f32_e32 v102, v73, v45
	v_fma_f32 v107, v40, v133, v32
	v_mul_f32_e32 v116, 0xbfb8aa3b, v102
	v_exp_f32_e32 v161, v116
	s_nop 0
	v_add_f32_e32 v160, 1.0, v161
	v_rcp_f32_e32 v88, v160
	s_nop 0
	v_mul_f32_e32 v101, v102, v88
	v_mov_b32_dpp v102, v6 row_ror:2 row_mask:0xf bank_mask:0xf
	v_mul_f32_e32 v109, v69, v101
	v_mov_b32_dpp v101, v6 row_ror:1 row_mask:0xf bank_mask:0xf
	v_mov_b32_dpp v102, v74 row_shr:2 row_mask:0xf bank_mask:0xf
	s_nop 0
	v_mov_b32_dpp v101, v74 row_shr:1 row_mask:0xf bank_mask:0xf
	v_fma_f32 v167, v30, v102, v26
	v_fmac_f32_e32 v167, v38, v101
	v_fmac_f32_e32 v167, v74, v46
	v_mul_f32_e32 v128, 0xbfb8aa3b, v167
	v_exp_f32_e32 v103, v128
	s_nop 0
	v_add_f32_e32 v140, 1.0, v103
	v_rcp_f32_e32 v66, v140
	s_nop 0
	v_mul_f32_e32 v100, v167, v66
	v_mov_b32_dpp v167, v7 row_ror:2 row_mask:0xf bank_mask:0xf
	v_mul_f32_e32 v253, v153, v100
	v_mov_b32_dpp v100, v7 row_ror:1 row_mask:0xf bank_mask:0xf
	v_mov_b32_dpp v167, v75 row_shr:2 row_mask:0xf bank_mask:0xf
	s_nop 0
	v_mov_b32_dpp v100, v75 row_shr:1 row_mask:0xf bank_mask:0xf
	v_fma_f32 v121, v31, v167, v27
	v_fmac_f32_e32 v121, v39, v100
	v_fmac_f32_e32 v121, v75, v47
	v_mul_f32_e32 v174, 0xbfb8aa3b, v121
	v_exp_f32_e32 v168, v174
	s_nop 0
	v_add_f32_e32 v136, 1.0, v168
	v_rcp_f32_e32 v67, v136
	s_nop 0
	v_mul_f32_e32 v89, v121, v67
	v_mov_b32_dpp v121, v16 row_ror:2 row_mask:0xf bank_mask:0xf
	v_mul_f32_e32 v156, v149, v89
	v_mov_b32_dpp v89, v16 row_ror:1 row_mask:0xf bank_mask:0xf
	v_mov_b32_dpp v121, v4 row_shr:2 row_mask:0xf bank_mask:0xf
	s_nop 0
	v_mov_b32_dpp v89, v4 row_shr:1 row_mask:0xf bank_mask:0xf
	v_fma_f32 v177, v28, v121, v24
	v_fmac_f32_e32 v177, v36, v89
	v_mov_b32_dpp v89, v8 row_ror:1 row_mask:0xf bank_mask:0xf
	v_fmac_f32_e32 v177, v4, v44
	s_nop 0
	v_mov_b32_dpp v89, v0 row_shr:1 row_mask:0xf bank_mask:0xf
	v_mul_f32_e32 v145, 0xbfb8aa3b, v177
	v_fmac_f32_e32 v107, v48, v89
	v_mov_b32_dpp v89, v17 row_ror:2 row_mask:0xf bank_mask:0xf
	v_exp_f32_e32 v175, v145
	v_fmac_f32_e32 v107, v0, v52
	v_mov_b32_dpp v89, v5 row_shr:2 row_mask:0xf bank_mask:0xf
	v_add_f32_e32 v62, 1.0, v175
	v_mov_b32_e32 v0, 0
	v_fma_f32 v112, v29, v89, v25
	v_rcp_f32_e32 v118, v62
	s_nop 0
	v_mul_f32_e32 v58, v177, v118
	v_mov_b32_dpp v177, v9 row_ror:2 row_mask:0xf bank_mask:0xf
	v_mul_f32_e32 v119, v107, v58
	v_mov_b32_dpp v58, v17 row_ror:1 row_mask:0xf bank_mask:0xf
	v_mov_b32_dpp v177, v1 row_shr:2 row_mask:0xf bank_mask:0xf
	s_nop 0
	v_mov_b32_dpp v58, v5 row_shr:1 row_mask:0xf bank_mask:0xf
	v_fma_f32 v59, v41, v177, v33
	v_fmac_f32_e32 v112, v37, v58
	v_mov_b32_e32 v58, 0
	v_fmac_f32_e32 v112, v5, v45
	v_mov_b32_dpp v5, v9 row_ror:1 row_mask:0xf bank_mask:0xf
	v_mul_f32_e32 v110, 0xbfb8aa3b, v112
	s_nop 0
	v_mov_b32_dpp v5, v1 row_shr:1 row_mask:0xf bank_mask:0xf
	v_exp_f32_e32 v84, v110
	v_fmac_f32_e32 v59, v49, v5
	v_add_f32_e32 v129, 1.0, v84
	v_fmac_f32_e32 v59, v1, v53
	v_mov_b32_dpp v1, v18 row_ror:2 row_mask:0xf bank_mask:0xf
	v_rcp_f32_e32 v137, v129
	s_nop 0
	v_mov_b32_dpp v1, v6 row_shr:2 row_mask:0xf bank_mask:0xf
	v_mul_f32_e32 v125, v112, v137
	v_fma_f32 v81, v30, v1, v26
	v_mov_b32_dpp v112, v10 row_ror:2 row_mask:0xf bank_mask:0xf
	v_mul_f32_e32 v182, v59, v125
	v_mov_b32_dpp v125, v18 row_ror:1 row_mask:0xf bank_mask:0xf
	v_mov_b32_dpp v112, v2 row_shr:2 row_mask:0xf bank_mask:0xf
	v_mov_b32_e32 v59, 0
	v_mov_b32_dpp v125, v6 row_shr:1 row_mask:0xf bank_mask:0xf
	v_fma_f32 v146, v42, v112, v34
	v_mov_b32_e32 v1, 0
	v_fmac_f32_e32 v81, v38, v125
	v_fmac_f32_e32 v81, v6, v46
	v_mov_b32_dpp v6, v10 row_ror:1 row_mask:0xf bank_mask:0xf
	v_mul_f32_e32 v180, 0xbfb8aa3b, v81
	s_nop 0
	v_mov_b32_dpp v6, v2 row_shr:1 row_mask:0xf bank_mask:0xf
	v_exp_f32_e32 v80, v180
	v_fmac_f32_e32 v146, v50, v6
	v_add_f32_e32 v63, 1.0, v80
	v_fmac_f32_e32 v146, v2, v54
	v_mov_b32_dpp v2, v11 row_ror:1 row_mask:0xf bank_mask:0xf
	v_rcp_f32_e32 v85, v63
	s_nop 0
	v_mov_b32_dpp v2, v3 row_shr:1 row_mask:0xf bank_mask:0xf
	v_mul_f32_e32 v122, v81, v85
	v_mov_b32_dpp v81, v19 row_ror:2 row_mask:0xf bank_mask:0xf
	v_mul_f32_e32 v6, v146, v122
	v_mov_b32_dpp v122, v19 row_ror:1 row_mask:0xf bank_mask:0xf
	v_mov_b32_dpp v81, v7 row_shr:2 row_mask:0xf bank_mask:0xf
	s_nop 0
	v_mov_b32_dpp v122, v7 row_shr:1 row_mask:0xf bank_mask:0xf
	v_fma_f32 v114, v31, v81, v27
	v_fmac_f32_e32 v114, v39, v122
	v_fmac_f32_e32 v114, v7, v47
	v_mov_b32_dpp v7, v11 row_ror:2 row_mask:0xf bank_mask:0xf
	v_mul_f32_e32 v60, 0xbfb8aa3b, v114
	s_nop 0
	v_mov_b32_dpp v7, v3 row_shr:2 row_mask:0xf bank_mask:0xf
	v_exp_f32_e32 v142, v60
	v_fma_f32 v189, v43, v7, v35
	v_add_f32_e32 v82, 1.0, v142
	v_fmac_f32_e32 v189, v51, v2
	v_mov_b32_dpp v2, v12 row_ror:1 row_mask:0xf bank_mask:0xf
	v_rcp_f32_e32 v173, v82
	v_fmac_f32_e32 v189, v3, v55
	v_mov_b32_dpp v2, v8 row_shr:1 row_mask:0xf bank_mask:0xf
	v_mul_f32_e32 v64, v114, v173
	v_mov_b32_dpp v114, v20 row_ror:2 row_mask:0xf bank_mask:0xf
	v_mov_b32_dpp v3, v12 row_ror:2 row_mask:0xf bank_mask:0xf
	v_mul_f32_e32 v7, v189, v64
	v_mov_b32_dpp v64, v20 row_ror:1 row_mask:0xf bank_mask:0xf
	v_mov_b32_dpp v114, v16 row_shr:2 row_mask:0xf bank_mask:0xf
	v_mov_b32_dpp v3, v8 row_shr:2 row_mask:0xf bank_mask:0xf
	v_mov_b32_dpp v64, v16 row_shr:1 row_mask:0xf bank_mask:0xf
	v_fma_f32 v86, v28, v114, v24
	v_fma_f32 v134, v40, v3, v32
	v_mov_b32_e32 v3, 0
	v_fmac_f32_e32 v86, v36, v64
	v_fmac_f32_e32 v134, v48, v2
	v_mov_b32_dpp v2, v13 row_ror:1 row_mask:0xf bank_mask:0xf
	v_fmac_f32_e32 v86, v16, v44
	v_fmac_f32_e32 v134, v8, v52
	v_mov_b32_dpp v2, v9 row_shr:1 row_mask:0xf bank_mask:0xf
	v_mul_f32_e32 v126, 0xbfb8aa3b, v86
	v_exp_f32_e32 v130, v126
	s_nop 0
	v_add_f32_e32 v65, 1.0, v130
	v_rcp_f32_e32 v94, v65
	s_nop 0
	v_mul_f32_e32 v57, v86, v94
	v_mov_b32_dpp v86, v21 row_ror:2 row_mask:0xf bank_mask:0xf
	v_mul_f32_e32 v83, v134, v57
	v_mov_b32_dpp v57, v21 row_ror:1 row_mask:0xf bank_mask:0xf
	v_mov_b32_dpp v86, v17 row_shr:2 row_mask:0xf bank_mask:0xf
	v_mov_b32_dpp v134, v13 row_ror:2 row_mask:0xf bank_mask:0xf
	v_mov_b32_dpp v57, v17 row_shr:1 row_mask:0xf bank_mask:0xf
	v_fma_f32 v99, v29, v86, v25
	v_mov_b32_dpp v134, v9 row_shr:2 row_mask:0xf bank_mask:0xf
	v_fmac_f32_e32 v99, v37, v57
	v_fma_f32 v147, v41, v134, v33
	v_mov_b32_e32 v57, 0
	v_fmac_f32_e32 v99, v17, v45
	v_fmac_f32_e32 v147, v49, v2
	v_mov_b32_dpp v2, v14 row_ror:1 row_mask:0xf bank_mask:0xf
	v_mul_f32_e32 v98, 0xbfb8aa3b, v99
	v_fmac_f32_e32 v147, v9, v53
	v_mov_b32_dpp v2, v10 row_shr:1 row_mask:0xf bank_mask:0xf
	v_exp_f32_e32 v115, v98
	s_nop 0
	v_add_f32_e32 v87, 1.0, v115
	v_rcp_f32_e32 v155, v87
	s_nop 0
	v_mul_f32_e32 v164, v99, v155
	v_mov_b32_dpp v99, v22 row_ror:2 row_mask:0xf bank_mask:0xf
	v_mul_f32_e32 v165, v147, v164
	v_mov_b32_dpp v164, v22 row_ror:1 row_mask:0xf bank_mask:0xf
	v_mov_b32_dpp v99, v18 row_shr:2 row_mask:0xf bank_mask:0xf
	v_mov_b32_dpp v147, v14 row_ror:2 row_mask:0xf bank_mask:0xf
	v_mov_b32_dpp v164, v18 row_shr:1 row_mask:0xf bank_mask:0xf
	v_fma_f32 v96, v30, v99, v26
	v_mov_b32_dpp v147, v10 row_shr:2 row_mask:0xf bank_mask:0xf
	v_fmac_f32_e32 v96, v38, v164
	v_fma_f32 v163, v42, v147, v34
	v_fmac_f32_e32 v96, v18, v46
	v_fmac_f32_e32 v163, v50, v2
	v_mov_b32_dpp v2, v15 row_ror:1 row_mask:0xf bank_mask:0xf
	v_mul_f32_e32 v97, 0xbfb8aa3b, v96
	v_fmac_f32_e32 v163, v10, v54
	v_mov_b32_dpp v2, v11 row_shr:1 row_mask:0xf bank_mask:0xf
	v_exp_f32_e32 v162, v97
	s_nop 0
	v_add_f32_e32 v143, 1.0, v162
	v_rcp_f32_e32 v152, v143
	s_nop 0
	v_mul_f32_e32 v72, v96, v152
	v_mov_b32_dpp v96, v23 row_ror:2 row_mask:0xf bank_mask:0xf
	v_mul_f32_e32 v10, v163, v72
	v_mov_b32_dpp v72, v23 row_ror:1 row_mask:0xf bank_mask:0xf
	v_mov_b32_dpp v96, v19 row_shr:2 row_mask:0xf bank_mask:0xf
	v_mov_b32_dpp v163, v15 row_ror:2 row_mask:0xf bank_mask:0xf
	v_mov_b32_dpp v72, v19 row_shr:1 row_mask:0xf bank_mask:0xf
	v_fma_f32 v135, v31, v96, v27
	v_mov_b32_dpp v163, v11 row_shr:2 row_mask:0xf bank_mask:0xf
	v_fmac_f32_e32 v135, v39, v72
	v_fma_f32 v123, v43, v163, v35
	v_fmac_f32_e32 v135, v19, v47
	v_fmac_f32_e32 v123, v51, v2
	v_mov_b32_e32 v2, 0
	v_mul_f32_e32 v151, 0xbfb8aa3b, v135
	v_fmac_f32_e32 v123, v11, v55
	v_exp_f32_e32 v76, v151
	s_nop 0
	v_add_f32_e32 v127, 1.0, v76
	v_rcp_f32_e32 v68, v127
	s_nop 0
	v_mul_f32_e32 v139, v135, v68
	v_mul_f32_e32 v11, v123, v139
	s_and_saveexec_b64 s[58:59], s[4:5]
	s_cbranch_execz .LBB0_593
	ds_read_b128 v[56:59], v244 offset:16
	ds_read_b128 v[0:3], v244 offset:528
.LBB0_593:
	s_or_b64 exec, exec, s[58:59]
	s_waitcnt lgkmcnt(1)
	v_mov_b32_dpp v17, v56 row_ror:1 row_mask:0xf bank_mask:0xf
	v_mov_b32_dpp v19, v56 row_ror:2 row_mask:0xf bank_mask:0xf
	s_nop 0
	v_mov_b32_dpp v17, v20 row_shr:1 row_mask:0xf bank_mask:0xf
	v_mov_b32_dpp v19, v20 row_shr:2 row_mask:0xf bank_mask:0xf
	s_waitcnt lgkmcnt(0)
	v_mov_b32_dpp v16, v0 row_ror:1 row_mask:0xf bank_mask:0xf
	v_mov_b32_dpp v18, v0 row_ror:2 row_mask:0xf bank_mask:0xf
	v_mov_b32_e32 v76, v40
	v_mov_b32_dpp v16, v12 row_shr:1 row_mask:0xf bank_mask:0xf
	v_mov_b32_dpp v18, v12 row_shr:2 row_mask:0xf bank_mask:0xf
	v_mov_b32_e32 v77, v28
	v_mov_b32_e32 v78, v32
	v_mov_b32_e32 v79, v24
	v_mov_b32_e32 v72, v12
	v_mov_b32_e32 v73, v20
	v_pk_fma_f32 v[18:19], v[76:77], v[18:19], v[78:79]
	v_mov_b32_e32 v76, v48
	v_mov_b32_e32 v77, v36
	v_mov_b32_e32 v74, v52
	v_mov_b32_e32 v75, v44
	v_pk_fma_f32 v[16:17], v[76:77], v[16:17], v[18:19]
	v_mov_b32_e32 v28, v41
	v_mov_b32_e32 v24, v33
	v_pk_fma_f32 v[16:17], v[72:73], v[74:75], v[16:17]
	v_mov_b32_e32 v36, v49
	v_mov_b32_e32 v20, v13
	v_mul_f32_e32 v90, 0xbfb8aa3b, v17
	v_mov_b32_e32 v44, v53
	v_mov_b32_dpp v19, v57 row_ror:2 row_mask:0xf bank_mask:0xf
	v_exp_f32_e32 v120, v90
	s_nop 0
	v_mov_b32_dpp v19, v21 row_shr:2 row_mask:0xf bank_mask:0xf
	v_mov_b32_dpp v18, v1 row_ror:2 row_mask:0xf bank_mask:0xf
	v_add_f32_e32 v116, 1.0, v120
	s_andn2_b64 vcc, exec, s[6:7]
	v_mov_b32_dpp v18, v13 row_shr:2 row_mask:0xf bank_mask:0xf
	v_rcp_f32_e32 v61, v116
	s_mov_b64 s[6:7], -1
	v_mul_f32_e32 v161, v17, v61
	v_mov_b32_dpp v17, v57 row_ror:1 row_mask:0xf bank_mask:0xf
	v_mul_f32_e32 v160, v16, v161
	s_nop 0
	v_mov_b32_dpp v17, v21 row_shr:1 row_mask:0xf bank_mask:0xf
	v_mov_b32_dpp v16, v1 row_ror:1 row_mask:0xf bank_mask:0xf
	v_pk_fma_f32 v[0:1], v[28:29], v[18:19], v[24:25]
	v_mov_b32_e32 v24, v34
	v_mov_b32_dpp v16, v13 row_shr:1 row_mask:0xf bank_mask:0xf
	v_mov_b32_e32 v25, v26
	v_mov_b32_e32 v18, v54
	v_pk_fma_f32 v[0:1], v[36:37], v[16:17], v[0:1]
	v_mov_b32_e32 v16, v14
	v_mov_b32_e32 v17, v22
	v_pk_fma_f32 v[0:1], v[20:21], v[44:45], v[0:1]
	v_mov_b32_e32 v20, v42
	v_mov_b32_e32 v21, v30
	v_mul_f32_e32 v88, 0xbfb8aa3b, v1
	v_mov_b32_e32 v19, v46
	v_mov_b32_e32 v30, v43
	v_exp_f32_e32 v69, v88
	v_mov_b32_dpp v13, v58 row_ror:2 row_mask:0xf bank_mask:0xf
	v_mov_b32_e32 v26, v35
	v_add_f32_e32 v102, 1.0, v69
	v_mov_b32_dpp v13, v22 row_shr:2 row_mask:0xf bank_mask:0xf
	v_mov_b32_e32 v46, v55
	v_rcp_f32_e32 v12, v102
	s_nop 0
	v_mul_f32_e32 v1, v1, v12
	v_mov_b32_dpp v12, v2 row_ror:2 row_mask:0xf bank_mask:0xf
	v_mul_f32_e32 v101, v0, v1
	v_mov_b32_dpp v1, v58 row_ror:1 row_mask:0xf bank_mask:0xf
	v_mov_b32_dpp v0, v2 row_ror:1 row_mask:0xf bank_mask:0xf
	v_mov_b32_dpp v12, v14 row_shr:2 row_mask:0xf bank_mask:0xf
	v_mov_b32_dpp v1, v22 row_shr:1 row_mask:0xf bank_mask:0xf
	v_mov_b32_dpp v0, v14 row_shr:1 row_mask:0xf bank_mask:0xf
	v_pk_fma_f32 v[12:13], v[20:21], v[12:13], v[24:25]
	v_mov_b32_e32 v20, v50
	v_mov_b32_e32 v21, v38
	v_mov_b32_e32 v38, v51
	v_mov_b32_e32 v22, v15
	v_pk_fma_f32 v[0:1], v[20:21], v[0:1], v[12:13]
	v_mov_b32_dpp v13, v59 row_ror:2 row_mask:0xf bank_mask:0xf
	v_mov_b32_dpp v12, v3 row_ror:2 row_mask:0xf bank_mask:0xf
	v_pk_fma_f32 v[0:1], v[16:17], v[18:19], v[0:1]
	v_mov_b32_dpp v13, v23 row_shr:2 row_mask:0xf bank_mask:0xf
	v_mov_b32_dpp v12, v15 row_shr:2 row_mask:0xf bank_mask:0xf
	v_mul_f32_e32 v128, 0xbfb8aa3b, v1
	v_lshlrev_b64 v[16:17], 1, v[220:221]
	v_exp_f32_e32 v70, v128
	s_nop 0
	v_add_f32_e32 v103, 1.0, v70
	v_rcp_f32_e32 v140, v103
	s_nop 0
	v_mul_f32_e32 v1, v1, v140
	v_mul_f32_e32 v66, v0, v1
	s_nop 0
	v_mov_b32_dpp v1, v59 row_ror:1 row_mask:0xf bank_mask:0xf
	v_mov_b32_dpp v0, v3 row_ror:1 row_mask:0xf bank_mask:0xf
	v_pk_fma_f32 v[2:3], v[30:31], v[12:13], v[26:27]
	v_mov_b32_dpp v1, v23 row_shr:1 row_mask:0xf bank_mask:0xf
	v_mov_b32_dpp v0, v15 row_shr:1 row_mask:0xf bank_mask:0xf
	v_mov_b64_e32 v[12:13], s[16:17]
	v_pk_fma_f32 v[0:1], v[38:39], v[0:1], v[2:3]
	v_mad_i64_i32 v[14:15], s[10:11], v222, s95, v[12:13]
	v_cvt_pk_bf16_f32 v2, v159, v150
	v_pk_fma_f32 v[0:1], v[22:23], v[46:47], v[0:1]
	v_lshl_add_u64 v[14:15], v[14:15], 0, v[16:17]
	v_cvt_pk_bf16_f32 v3, v138, v131
	v_mul_f32_e32 v153, 0xbfb8aa3b, v1
	v_exp_f32_e32 v167, v153
	s_nop 0
	v_add_f32_e32 v100, 1.0, v167
	v_rcp_f32_e32 v174, v100
	s_nop 0
	v_mul_f32_e32 v71, v1, v174
	v_cvt_pk_bf16_f32 v1, v176, v248
	v_mul_f32_e32 v168, v0, v71
	v_cvt_pk_bf16_f32 v0, v254, v158
	global_store_dwordx4 v[14:15], v[0:3], off
	s_nop 1
	v_mad_i64_i32 v[14:15], s[10:11], v224, s95, v[12:13]
	v_cvt_pk_bf16_f32 v0, v202, v223
	v_cvt_pk_bf16_f32 v1, v225, v227
	v_lshl_add_u64 v[14:15], v[14:15], 0, v[16:17]
	v_cvt_pk_bf16_f32 v2, v124, v117
	v_cvt_pk_bf16_f32 v3, v106, v111
	global_store_dwordx4 v[14:15], v[0:3], off
	s_nop 1
	v_mad_i64_i32 v[14:15], s[10:11], v226, s95, v[12:13]
	v_cvt_pk_bf16_f32 v0, v188, v187
	v_cvt_pk_bf16_f32 v1, v190, v191
	v_lshl_add_u64 v[14:15], v[14:15], 0, v[16:17]
	v_cvt_pk_bf16_f32 v2, v95, v166
	v_cvt_pk_bf16_f32 v3, v91, v144
	global_store_dwordx4 v[14:15], v[0:3], off
	s_nop 1
	v_mad_i64_i32 v[14:15], s[10:11], v228, s95, v[12:13]
	v_cvt_pk_bf16_f32 v0, v184, v185
	v_cvt_pk_bf16_f32 v1, v243, v242
	v_lshl_add_u64 v[14:15], v[14:15], 0, v[16:17]
	v_cvt_pk_bf16_f32 v2, v132, v141
	v_cvt_pk_bf16_f32 v3, v113, v154
	global_store_dwordx4 v[14:15], v[0:3], off
	s_nop 1
	v_mad_i64_i32 v[14:15], s[10:11], v230, s95, v[12:13]
	v_cvt_pk_bf16_f32 v0, v105, v171
	v_cvt_pk_bf16_f32 v1, v169, v148
	v_cvt_pk_bf16_f32 v2, v160, v101
	v_lshl_add_u64 v[14:15], v[14:15], 0, v[16:17]
	v_cvt_pk_bf16_f32 v3, v66, v168
	global_store_dwordx4 v[14:15], v[0:3], off
	s_nop 1
	v_cvt_pk_bf16_f32 v0, v93, v186
	v_cvt_pk_bf16_f32 v1, v179, v104
	v_cvt_pk_bf16_f32 v2, v83, v165
	v_mad_i64_i32 v[8:9], s[10:11], v232, s95, v[12:13]
	v_cvt_pk_bf16_f32 v3, v10, v11
	v_mad_i64_i32 v[4:5], s[10:11], v234, s95, v[12:13]
	v_lshl_add_u64 v[8:9], v[8:9], 0, v[16:17]
	global_store_dwordx4 v[8:9], v[0:3], off
	s_nop 1
	v_cvt_pk_bf16_f32 v0, v170, v178
	v_cvt_pk_bf16_f32 v1, v92, v181
	v_cvt_pk_bf16_f32 v2, v119, v182
	v_lshl_add_u64 v[4:5], v[4:5], 0, v[16:17]
	v_cvt_pk_bf16_f32 v3, v6, v7
	global_store_dwordx4 v[4:5], v[0:3], off
	s_nop 1
	v_mad_i64_i32 v[4:5], s[10:11], v236, s95, v[12:13]
	v_cvt_pk_bf16_f32 v0, v252, v183
	v_cvt_pk_bf16_f32 v1, v172, v157
	v_lshl_add_u64 v[4:5], v[4:5], 0, v[16:17]
	v_cvt_pk_bf16_f32 v2, v108, v109
	v_cvt_pk_bf16_f32 v3, v253, v156
	global_store_dwordx4 v[4:5], v[0:3], off
	s_cbranch_vccnz .LBB0_573
	s_and_b64 vcc, exec, s[8:9]
	s_cbranch_vccnz .LBB0_572
	s_barrier
	s_branch .LBB0_572
